# adds: memory-attention Q fragments prefetched 4 steps ahead (counted waits); in-proj tile boundary: early next-tile A11 LDS-DMA before the epilogue stores and vmcnt(24) in P0-P2 of the first K-iterati
# baseline (speedup 1.0000x reference)
; #define PG8_STAGE(bufoff, gbase, voff) do { unsigned _g = (gbase); asm volatile("" : "+s"(_g));   _Pragma("unroll") for (int _i = 0; _i < 2; ++_i) \
;         __builtin_amdgcn_global_load_lds((const unsigned*)(wsb + (size_t)(unsigned)(_g + (voff)[_i])), (LAS unsigned*)(lds + (bufoff) + ldsw + _i * 8192), 16, 0, 0); } while (0)
; #define PG8_WAIT_V(n) asm volatile("s_waitcnt vmcnt(" #n ")" ::: "memory")
; #define PG8_WAIT_L(n) asm volatile("s_waitcnt lgkmcnt(" #n ")" ::: "memory")
; #define PG8_BAR __builtin_amdgcn_s_barrier()
; #define PG8_SCHED __builtin_amdgcn_sched_barrier(0)
;     ...
;             PG8_LDB(B0, 0, 0); PG8_LDB(B1, 0, 1); PG8_SCHED; PG8_LDA(At, 0, 0); PG8_STAGE(PG8_SA(1, 1), a1 + hstep, voffA);
;             PG8_WAIT_V(8); PG8_WAIT_L(0); PG8_BAR; PG8_MMA(0, 0, At, B0); PG8_MMA(0, 1, At, B1); PG8_BAR; PG8_SCHED;
.Lin_g2_first:
	s_cmp_eq_u32 s86, 1
	s_cbranch_scc1 .Lin_g2_norm
	s_waitcnt vmcnt(24)
	s_branch .Lin_g2_join

; #define PG8_STAGE(bufoff, gbase, voff) do { unsigned _g = (gbase); asm volatile("" : "+s"(_g));   _Pragma("unroll") for (int _i = 0; _i < 2; ++_i) \
;         __builtin_amdgcn_global_load_lds((const unsigned*)(wsb + (size_t)(unsigned)(_g + (voff)[_i])), (LAS unsigned*)(lds + (bufoff) + ldsw + _i * 8192), 16, 0, 0); } while (0)
; #define PG8_SCHED __builtin_amdgcn_sched_barrier(0)
;     ...
;             PG8_LDB(B0, 0, 0); PG8_LDB(B1, 0, 1); PG8_SCHED; PG8_LDA(At, 0, 0); PG8_STAGE(PG8_SA(1, 1), a1 + hstep, voffA);
.Lin_epi_fast:
	s_and_b64 vcc, exec, s[36:37]
	s_cbranch_vccnz .Lin_noearly_a
	s_add_i32 s82, s90, 0x100080
	s_add_i32 m0, s38, 0xc000
	v_mov_b32_e32 v163, 0
	v_add_u32_e32 v162, s82, v148
	v_lshl_add_u64 v[146:147], v[130:131], 0, v[162:163]
	v_add_u32_e32 v162, s82, v150
	global_load_lds_dwordx4 v[146:147], off
	v_lshl_add_u64 v[146:147], v[130:131], 0, v[162:163]
	s_add_i32 m0, s38, 0xe000
	s_nop 0
	global_load_lds_dwordx4 v[146:147], off

; #define PG8_STAGE(bufoff, gbase, voff) do { unsigned _g = (gbase); asm volatile("" : "+s"(_g));   _Pragma("unroll") for (int _i = 0; _i < 2; ++_i) \
;         __builtin_amdgcn_global_load_lds((const unsigned*)(wsb + (size_t)(unsigned)(_g + (voff)[_i])), (LAS unsigned*)(lds + (bufoff) + ldsw + _i * 8192), 16, 0, 0); } while (0)
; #define PG8_WAIT_V(n) asm volatile("s_waitcnt vmcnt(" #n ")" ::: "memory")
; #define PG8_WAIT_L(n) asm volatile("s_waitcnt lgkmcnt(" #n ")" ::: "memory")
; #define PG8_BAR __builtin_amdgcn_s_barrier()
; #define PG8_SCHED __builtin_amdgcn_sched_barrier(0)
;     ...
;             PG8_LDB(B0, 0, 0); PG8_LDB(B1, 0, 1); PG8_SCHED; PG8_LDA(At, 0, 0); PG8_STAGE(PG8_SA(1, 1), a1 + hstep, voffA);
;             PG8_WAIT_V(8); PG8_WAIT_L(0); PG8_BAR; PG8_MMA(0, 0, At, B0); PG8_MMA(0, 1, At, B1); PG8_BAR; PG8_SCHED;
;             PG8_LDA(At, 0, 1); PG8_STAGE(PG8_SB(0, 0), b2, voffB); PG8_STAGE(PG8_SB(0, 1), b2 + hstep, voffB); PG8_STAGE(PG8_SA(0, 0), a2, voffA);
;             PG8_WAIT_V(8); PG8_WAIT_L(0); PG8_BAR; PG8_MMA(1, 0, At, B0); PG8_MMA(1, 1, At, B1); PG8_BAR; PG8_SCHED;
.LBB0_279:
	s_add_i32 s11, s8, 0xfff00080
	s_cmp_eq_u32 s10, 60
	s_cselect_b32 s83, s4, s11
	s_cselect_b32 s82, s5, s9
	s_add_i32 s84, 0, 0x10000
	v_add_u32_e32 v0, s84, v152
	s_add_i32 s96, 0, 0x14000
	ds_read_b128 v[138:141], v0
	ds_read_b128 v[142:145], v0 offset:1024
	ds_read_b128 v[154:157], v0 offset:2048
	ds_read_b128 v[158:161], v0 offset:3072
	v_add_u32_e32 v0, s96, v152
	ds_read_b128 v[162:165], v0
	ds_read_b128 v[166:169], v0 offset:1024
	ds_read_b128 v[170:173], v0 offset:2048
	ds_read_b128 v[174:177], v0 offset:3072
	s_add_i32 s11, s83, 0x80
	s_mov_b32 s97, s8
	ds_read_b128 v[178:181], v153
	ds_read_b128 v[182:185], v153 offset:1024
	ds_read_b128 v[186:189], v153 offset:2048
	ds_read_b128 v[190:193], v153 offset:3072
	ds_read_b128 v[194:197], v153 offset:4096
	ds_read_b128 v[198:201], v153 offset:5120
	ds_read_b128 v[202:205], v153 offset:6144
	ds_read_b128 v[206:209], v153 offset:7168
	s_cmp_eq_i32 s10, -2
	s_cbranch_scc1 .Lin_g0_first
.Lin_g0_norm:
	s_add_i32 m0, s38, 0xc000
	v_add_u32_e32 v0, s97, v148
	v_lshl_add_u64 v[146:147], v[130:131], 0, v[0:1]
	v_add_u32_e32 v0, s97, v150
	global_load_lds_dwordx4 v[146:147], off
	v_lshl_add_u64 v[146:147], v[130:131], 0, v[0:1]
	s_add_i32 m0, s38, 0xe000
	s_nop 0
	global_load_lds_dwordx4 v[146:147], off
	s_waitcnt vmcnt(8)
.Lin_g0_join:
	s_waitcnt lgkmcnt(0)
	s_barrier
	s_setprio 1
	s_waitcnt lgkmcnt(0)
	v_mfma_f32_16x16x32_bf16 v[126:129], v[138:141], v[178:181], v[126:129]
	v_mfma_f32_16x16x32_bf16 v[122:125], v[154:157], v[178:181], v[122:125]
	v_mfma_f32_16x16x32_bf16 v[110:113], v[138:141], v[186:189], v[110:113]
	v_mfma_f32_16x16x32_bf16 v[106:109], v[154:157], v[186:189], v[106:109]
	v_mfma_f32_16x16x32_bf16 v[94:97], v[138:141], v[194:197], v[94:97]
	v_mfma_f32_16x16x32_bf16 v[90:93], v[154:157], v[194:197], v[90:93]
	v_mfma_f32_16x16x32_bf16 v[78:81], v[138:141], v[202:205], v[78:81]
	v_mfma_f32_16x16x32_bf16 v[74:77], v[154:157], v[202:205], v[74:77]
	v_mfma_f32_16x16x32_bf16 v[126:129], v[142:145], v[182:185], v[126:129]
	v_mfma_f32_16x16x32_bf16 v[122:125], v[158:161], v[182:185], v[122:125]
	v_mfma_f32_16x16x32_bf16 v[110:113], v[142:145], v[190:193], v[110:113]
	v_mfma_f32_16x16x32_bf16 v[106:109], v[158:161], v[190:193], v[106:109]
	v_mfma_f32_16x16x32_bf16 v[94:97], v[142:145], v[198:201], v[94:97]
	v_mfma_f32_16x16x32_bf16 v[90:93], v[158:161], v[198:201], v[90:93]
	v_mfma_f32_16x16x32_bf16 v[78:81], v[142:145], v[206:209], v[78:81]
	v_mfma_f32_16x16x32_bf16 v[74:77], v[158:161], v[206:209], v[74:77]
	s_setprio 0
	s_setprio 1
	v_mfma_f32_16x16x32_bf16 v[118:121], v[162:165], v[178:181], v[118:121]
	v_mfma_f32_16x16x32_bf16 v[114:117], v[170:173], v[178:181], v[114:117]
	v_mfma_f32_16x16x32_bf16 v[102:105], v[162:165], v[186:189], v[102:105]
	v_mfma_f32_16x16x32_bf16 v[98:101], v[170:173], v[186:189], v[98:101]
	v_mfma_f32_16x16x32_bf16 v[86:89], v[162:165], v[194:197], v[86:89]
	v_mfma_f32_16x16x32_bf16 v[82:85], v[170:173], v[194:197], v[82:85]
	v_mfma_f32_16x16x32_bf16 v[70:73], v[162:165], v[202:205], v[70:73]
	v_mfma_f32_16x16x32_bf16 v[66:69], v[170:173], v[202:205], v[66:69]
	v_mfma_f32_16x16x32_bf16 v[118:121], v[166:169], v[182:185], v[118:121]
	v_mfma_f32_16x16x32_bf16 v[114:117], v[174:177], v[182:185], v[114:117]
	v_mfma_f32_16x16x32_bf16 v[102:105], v[166:169], v[190:193], v[102:105]
	v_mfma_f32_16x16x32_bf16 v[98:101], v[174:177], v[190:193], v[98:101]
	v_mfma_f32_16x16x32_bf16 v[86:89], v[166:169], v[198:201], v[86:89]
	v_mfma_f32_16x16x32_bf16 v[82:85], v[174:177], v[198:201], v[82:85]
	v_mfma_f32_16x16x32_bf16 v[70:73], v[166:169], v[206:209], v[70:73]
	v_mfma_f32_16x16x32_bf16 v[66:69], v[174:177], v[206:209], v[66:69]
	s_setprio 0
	s_barrier
	s_mov_b32 s97, s82
	ds_read_b128 v[178:181], v153 offset:16384
	ds_read_b128 v[182:185], v153 offset:17408
	ds_read_b128 v[186:189], v153 offset:18432
	ds_read_b128 v[190:193], v153 offset:19456
	ds_read_b128 v[194:197], v153 offset:20480
	ds_read_b128 v[198:201], v153 offset:21504
	ds_read_b128 v[202:205], v153 offset:22528
	ds_read_b128 v[206:209], v153 offset:23552
	s_add_i32 s84, s84, s7
	v_add_u32_e32 v0, s97, v149
	v_lshl_add_u64 v[146:147], v[130:131], 0, v[0:1]
	s_mov_b32 m0, s84
	v_add_u32_e32 v0, s97, v151
	global_load_lds_dwordx4 v[146:147], off
	v_lshl_add_u64 v[146:147], v[130:131], 0, v[0:1]
	s_add_i32 m0, s84, 0x2000
	s_add_i32 s84, s82, 0x100000
	global_load_lds_dwordx4 v[146:147], off
	s_add_i32 s96, s96, s7
	v_add_u32_e32 v0, s84, v149
	v_lshl_add_u64 v[146:147], v[130:131], 0, v[0:1]
	s_mov_b32 m0, s96
	v_add_u32_e32 v0, s84, v151
	global_load_lds_dwordx4 v[146:147], off
	v_lshl_add_u64 v[146:147], v[130:131], 0, v[0:1]
	s_add_i32 m0, s96, 0x2000
	s_mov_b32 s84, s83
	global_load_lds_dwordx4 v[146:147], off
	s_mov_b32 m0, s38
	v_add_u32_e32 v0, s84, v148
	v_lshl_add_u64 v[146:147], v[130:131], 0, v[0:1]
	v_add_u32_e32 v0, s84, v150
	global_load_lds_dwordx4 v[146:147], off
	v_lshl_add_u64 v[146:147], v[130:131], 0, v[0:1]
	s_mov_b32 m0, s39
	s_nop 0
	global_load_lds_dwordx4 v[146:147], off
	s_cmp_eq_i32 s10, -2
	s_cbranch_scc1 .Lin_g1_first
; #define PG8_STAGE(bufoff, gbase, voff) do { unsigned _g = (gbase); asm volatile("" : "+s"(_g));   _Pragma("unroll") for (int _i = 0; _i < 2; ++_i) \
;         __builtin_amdgcn_global_load_lds((const unsigned*)(wsb + (size_t)(unsigned)(_g + (voff)[_i])), (LAS unsigned*)(lds + (bufoff) + ldsw + _i * 8192), 16, 0, 0); } while (0)
; #define PG8_WAIT_V(n) asm volatile("s_waitcnt vmcnt(" #n ")" ::: "memory")
; #define PG8_WAIT_L(n) asm volatile("s_waitcnt lgkmcnt(" #n ")" ::: "memory")
; #define PG8_BAR __builtin_amdgcn_s_barrier()
; #define PG8_SCHED __builtin_amdgcn_sched_barrier(0)
;     ...
;             PG8_WAIT_V(8); PG8_WAIT_L(0); PG8_BAR; PG8_MMA(1, 0, At, B0); PG8_MMA(1, 1, At, B1); PG8_BAR; PG8_SCHED;
;             PG8_LDB(B0, 1, 0); PG8_LDB(B1, 1, 1); PG8_SCHED; PG8_LDA(At, 1, 0); PG8_STAGE(PG8_SA(0, 1), a2 + hstep, voffA);
.Lin_g1_norm:
	s_waitcnt vmcnt(8)
.Lin_g1_join:
	s_waitcnt lgkmcnt(0)
	s_barrier
	s_setprio 1
	s_waitcnt lgkmcnt(0)
	v_mfma_f32_16x16x32_bf16 v[62:65], v[138:141], v[178:181], v[62:65]
	v_mfma_f32_16x16x32_bf16 v[58:61], v[154:157], v[178:181], v[58:61]
	v_mfma_f32_16x16x32_bf16 v[46:49], v[138:141], v[186:189], v[46:49]
	v_mfma_f32_16x16x32_bf16 v[42:45], v[154:157], v[186:189], v[42:45]
	v_mfma_f32_16x16x32_bf16 v[30:33], v[138:141], v[194:197], v[30:33]
	v_mfma_f32_16x16x32_bf16 v[26:29], v[154:157], v[194:197], v[26:29]
	v_mfma_f32_16x16x32_bf16 v[14:17], v[138:141], v[202:205], v[14:17]
	v_mfma_f32_16x16x32_bf16 v[10:13], v[154:157], v[202:205], v[10:13]
	v_mfma_f32_16x16x32_bf16 v[62:65], v[142:145], v[182:185], v[62:65]
	v_mfma_f32_16x16x32_bf16 v[58:61], v[158:161], v[182:185], v[58:61]
	v_mfma_f32_16x16x32_bf16 v[46:49], v[142:145], v[190:193], v[46:49]
	v_mfma_f32_16x16x32_bf16 v[42:45], v[158:161], v[190:193], v[42:45]
	v_mfma_f32_16x16x32_bf16 v[30:33], v[142:145], v[198:201], v[30:33]
	v_mfma_f32_16x16x32_bf16 v[26:29], v[158:161], v[198:201], v[26:29]
	v_mfma_f32_16x16x32_bf16 v[14:17], v[142:145], v[206:209], v[14:17]
	v_mfma_f32_16x16x32_bf16 v[10:13], v[158:161], v[206:209], v[10:13]
	s_setprio 0
	s_setprio 1
	v_mfma_f32_16x16x32_bf16 v[54:57], v[162:165], v[178:181], v[54:57]
	v_mfma_f32_16x16x32_bf16 v[50:53], v[170:173], v[178:181], v[50:53]
	v_mfma_f32_16x16x32_bf16 v[38:41], v[162:165], v[186:189], v[38:41]
	v_mfma_f32_16x16x32_bf16 v[34:37], v[170:173], v[186:189], v[34:37]
	v_mfma_f32_16x16x32_bf16 v[22:25], v[162:165], v[194:197], v[22:25]
	v_mfma_f32_16x16x32_bf16 v[18:21], v[170:173], v[194:197], v[18:21]
	v_mfma_f32_16x16x32_bf16 v[6:9], v[162:165], v[202:205], v[6:9]
	v_mfma_f32_16x16x32_bf16 v[2:5], v[170:173], v[202:205], v[2:5]
	v_mfma_f32_16x16x32_bf16 v[54:57], v[166:169], v[182:185], v[54:57]
	v_mfma_f32_16x16x32_bf16 v[50:53], v[174:177], v[182:185], v[50:53]
	v_mfma_f32_16x16x32_bf16 v[38:41], v[166:169], v[190:193], v[38:41]
	v_mfma_f32_16x16x32_bf16 v[34:37], v[174:177], v[190:193], v[34:37]
	v_mfma_f32_16x16x32_bf16 v[22:25], v[166:169], v[198:201], v[22:25]
	v_mfma_f32_16x16x32_bf16 v[18:21], v[174:177], v[198:201], v[18:21]
	v_mfma_f32_16x16x32_bf16 v[6:9], v[166:169], v[206:209], v[6:9]
	v_mfma_f32_16x16x32_bf16 v[2:5], v[174:177], v[206:209], v[2:5]
	s_setprio 0
	s_barrier
	s_add_i32 s84, 0, 0x18000
	v_add_u32_e32 v0, s84, v152
	s_add_i32 s96, 0, 0x1c000
	ds_read_b128 v[138:141], v0
	ds_read_b128 v[142:145], v0 offset:1024
	ds_read_b128 v[154:157], v0 offset:2048
	ds_read_b128 v[158:161], v0 offset:3072
	v_add_u32_e32 v0, s96, v152
	ds_read_b128 v[162:165], v0
	ds_read_b128 v[166:169], v0 offset:1024
	ds_read_b128 v[170:173], v0 offset:2048
	ds_read_b128 v[174:177], v0 offset:3072
	s_add_i32 s83, s83, 0x100000
	ds_read_b128 v[178:181], v153 offset:32768
	ds_read_b128 v[182:185], v153 offset:33792
	ds_read_b128 v[186:189], v153 offset:34816
	ds_read_b128 v[190:193], v153 offset:35840
	ds_read_b128 v[194:197], v153 offset:36864
	ds_read_b128 v[198:201], v153 offset:37888
	ds_read_b128 v[202:205], v153 offset:38912
	ds_read_b128 v[206:209], v153 offset:39936
	s_mov_b32 m0, s44
	v_add_u32_e32 v0, s83, v148
	v_lshl_add_u64 v[146:147], v[130:131], 0, v[0:1]
	v_add_u32_e32 v0, s83, v150
	global_load_lds_dwordx4 v[146:147], off
	v_lshl_add_u64 v[146:147], v[130:131], 0, v[0:1]
	s_mov_b32 m0, s45
	s_nop 0
	global_load_lds_dwordx4 v[146:147], off
	s_cmp_eq_i32 s10, -2
	s_cbranch_scc1 .Lin_g2_first

; __device__ __forceinline__ int lane_id_hw() { int l; asm volatile("v_mbcnt_lo_u32_b32 %0, -1, 0\n\tv_mbcnt_hi_u32_b32 %0, -1, %0" : "=v"(l)); return l; }
; #define PG8_STAGE(bufoff, gbase, voff) do { unsigned _g = (gbase); asm volatile("" : "+s"(_g));   _Pragma("unroll") for (int _i = 0; _i < 2; ++_i) \
;         __builtin_amdgcn_global_load_lds((const unsigned*)(wsb + (size_t)(unsigned)(_g + (voff)[_i])), (LAS unsigned*)(lds + (bufoff) + ldsw + _i * 8192), 16, 0, 0); } while (0)
; #define PG8_WAIT_V(n) asm volatile("s_waitcnt vmcnt(" #n ")" ::: "memory")
; #define PG8_WAIT_L(n) asm volatile("s_waitcnt lgkmcnt(" #n ")" ::: "memory")
; #define PG8_BAR __builtin_amdgcn_s_barrier()
; #define PG8_SCHED __builtin_amdgcn_sched_barrier(0)
;     ...
;         for (int t = 0; t < nt; t += 2) {
;     ...
;             PG8_LDB(B0, 1, 0); PG8_LDB(B1, 1, 1); PG8_SCHED; PG8_LDA(At, 1, 0); PG8_STAGE(PG8_SA(0, 1), a2 + hstep, voffA);
;             PG8_WAIT_V(8); PG8_WAIT_L(0); PG8_BAR; PG8_MMA(0, 0, At, B0); PG8_MMA(0, 1, At, B1); PG8_BAR; PG8_SCHED;
;             PG8_LDA(At, 1, 1); PG8_STAGE(PG8_SB(1, 0), b3, voffB); PG8_STAGE(PG8_SB(1, 1), b3 + hstep, voffB); PG8_STAGE(PG8_SA(1, 0), a3, voffA);
;             PG8_WAIT_V(8); PG8_WAIT_L(0); PG8_BAR; PG8_MMA(1, 0, At, B0); PG8_MMA(1, 1, At, B1); PG8_BAR; PG8_SCHED;
;     ...
;         { const int l2 = lane_id_hw(); E(acc, cur, wr, wc, l2 & 15, l2 >> 4); }
.Lin_g2_join:
	s_waitcnt lgkmcnt(0)
	s_barrier
	s_setprio 1
	s_waitcnt lgkmcnt(0)
	v_mfma_f32_16x16x32_bf16 v[126:129], v[138:141], v[178:181], v[126:129]
	v_mfma_f32_16x16x32_bf16 v[122:125], v[154:157], v[178:181], v[122:125]
	v_mfma_f32_16x16x32_bf16 v[110:113], v[138:141], v[186:189], v[110:113]
	v_mfma_f32_16x16x32_bf16 v[106:109], v[154:157], v[186:189], v[106:109]
	v_mfma_f32_16x16x32_bf16 v[94:97], v[138:141], v[194:197], v[94:97]
	v_mfma_f32_16x16x32_bf16 v[90:93], v[154:157], v[194:197], v[90:93]
	v_mfma_f32_16x16x32_bf16 v[78:81], v[138:141], v[202:205], v[78:81]
	v_mfma_f32_16x16x32_bf16 v[74:77], v[154:157], v[202:205], v[74:77]
	v_mfma_f32_16x16x32_bf16 v[126:129], v[142:145], v[182:185], v[126:129]
	v_mfma_f32_16x16x32_bf16 v[122:125], v[158:161], v[182:185], v[122:125]
	v_mfma_f32_16x16x32_bf16 v[110:113], v[142:145], v[190:193], v[110:113]
	v_mfma_f32_16x16x32_bf16 v[106:109], v[158:161], v[190:193], v[106:109]
	v_mfma_f32_16x16x32_bf16 v[94:97], v[142:145], v[198:201], v[94:97]
	v_mfma_f32_16x16x32_bf16 v[90:93], v[158:161], v[198:201], v[90:93]
	v_mfma_f32_16x16x32_bf16 v[78:81], v[142:145], v[206:209], v[78:81]
	v_mfma_f32_16x16x32_bf16 v[74:77], v[158:161], v[206:209], v[74:77]
	s_setprio 0
	s_setprio 1
	v_mfma_f32_16x16x32_bf16 v[118:121], v[162:165], v[178:181], v[118:121]
	v_mfma_f32_16x16x32_bf16 v[114:117], v[170:173], v[178:181], v[114:117]
	v_mfma_f32_16x16x32_bf16 v[102:105], v[162:165], v[186:189], v[102:105]
	v_mfma_f32_16x16x32_bf16 v[98:101], v[170:173], v[186:189], v[98:101]
	v_mfma_f32_16x16x32_bf16 v[86:89], v[162:165], v[194:197], v[86:89]
	v_mfma_f32_16x16x32_bf16 v[82:85], v[170:173], v[194:197], v[82:85]
	v_mfma_f32_16x16x32_bf16 v[70:73], v[162:165], v[202:205], v[70:73]
	v_mfma_f32_16x16x32_bf16 v[66:69], v[170:173], v[202:205], v[66:69]
	v_mfma_f32_16x16x32_bf16 v[118:121], v[166:169], v[182:185], v[118:121]
	v_mfma_f32_16x16x32_bf16 v[114:117], v[174:177], v[182:185], v[114:117]
	v_mfma_f32_16x16x32_bf16 v[102:105], v[166:169], v[190:193], v[102:105]
	v_mfma_f32_16x16x32_bf16 v[98:101], v[174:177], v[190:193], v[98:101]
	v_mfma_f32_16x16x32_bf16 v[86:89], v[166:169], v[198:201], v[86:89]
	v_mfma_f32_16x16x32_bf16 v[82:85], v[174:177], v[198:201], v[82:85]
	v_mfma_f32_16x16x32_bf16 v[70:73], v[166:169], v[206:209], v[70:73]
	v_mfma_f32_16x16x32_bf16 v[66:69], v[174:177], v[206:209], v[66:69]
	s_setprio 0
	s_barrier
	s_add_i32 s83, s82, 0x80
	ds_read_b128 v[178:181], v153 offset:49152
	ds_read_b128 v[182:185], v153 offset:50176
	ds_read_b128 v[186:189], v153 offset:51200
	ds_read_b128 v[190:193], v153 offset:52224
	ds_read_b128 v[194:197], v153 offset:53248
	ds_read_b128 v[198:201], v153 offset:54272
	ds_read_b128 v[202:205], v153 offset:55296
	ds_read_b128 v[206:209], v153 offset:56320
	s_add_i32 s84, s84, s7
	v_add_u32_e32 v0, s83, v149
	v_lshl_add_u64 v[146:147], v[130:131], 0, v[0:1]
	s_mov_b32 m0, s84
	v_add_u32_e32 v0, s83, v151
	global_load_lds_dwordx4 v[146:147], off
	v_lshl_add_u64 v[146:147], v[130:131], 0, v[0:1]
	s_add_i32 m0, s84, 0x2000
	s_add_i32 s82, s82, 0x100080
	global_load_lds_dwordx4 v[146:147], off
	s_add_i32 s83, s96, s7
	v_add_u32_e32 v0, s82, v149
	v_lshl_add_u64 v[146:147], v[130:131], 0, v[0:1]
	s_mov_b32 m0, s83
	v_add_u32_e32 v0, s82, v151
	global_load_lds_dwordx4 v[146:147], off
	v_lshl_add_u64 v[146:147], v[130:131], 0, v[0:1]
	s_add_i32 m0, s83, 0x2000
	s_nop 0
	global_load_lds_dwordx4 v[146:147], off
	s_mov_b32 m0, s46
	v_add_u32_e32 v0, s11, v148
	v_lshl_add_u64 v[146:147], v[130:131], 0, v[0:1]
	v_add_u32_e32 v0, s11, v150
	global_load_lds_dwordx4 v[146:147], off
	v_lshl_add_u64 v[146:147], v[130:131], 0, v[0:1]
	s_mov_b32 m0, s47
	s_nop 0
	global_load_lds_dwordx4 v[146:147], off
	s_waitcnt vmcnt(8)
	s_waitcnt lgkmcnt(0)
	s_barrier
	s_setprio 1
	s_waitcnt lgkmcnt(0)
	v_mfma_f32_16x16x32_bf16 v[62:65], v[138:141], v[178:181], v[62:65]
	v_mfma_f32_16x16x32_bf16 v[58:61], v[154:157], v[178:181], v[58:61]
	v_mfma_f32_16x16x32_bf16 v[46:49], v[138:141], v[186:189], v[46:49]
	v_mfma_f32_16x16x32_bf16 v[42:45], v[154:157], v[186:189], v[42:45]
	v_mfma_f32_16x16x32_bf16 v[30:33], v[138:141], v[194:197], v[30:33]
	v_mfma_f32_16x16x32_bf16 v[26:29], v[154:157], v[194:197], v[26:29]
	v_mfma_f32_16x16x32_bf16 v[14:17], v[138:141], v[202:205], v[14:17]
	v_mfma_f32_16x16x32_bf16 v[10:13], v[154:157], v[202:205], v[10:13]
	v_mfma_f32_16x16x32_bf16 v[62:65], v[142:145], v[182:185], v[62:65]
	v_mfma_f32_16x16x32_bf16 v[58:61], v[158:161], v[182:185], v[58:61]
	v_mfma_f32_16x16x32_bf16 v[46:49], v[142:145], v[190:193], v[46:49]
	v_mfma_f32_16x16x32_bf16 v[42:45], v[158:161], v[190:193], v[42:45]
	v_mfma_f32_16x16x32_bf16 v[30:33], v[142:145], v[198:201], v[30:33]
	v_mfma_f32_16x16x32_bf16 v[26:29], v[158:161], v[198:201], v[26:29]
	v_mfma_f32_16x16x32_bf16 v[14:17], v[142:145], v[206:209], v[14:17]
	v_mfma_f32_16x16x32_bf16 v[10:13], v[158:161], v[206:209], v[10:13]
	s_setprio 0
	s_setprio 1
	v_mfma_f32_16x16x32_bf16 v[54:57], v[162:165], v[178:181], v[54:57]
	v_mfma_f32_16x16x32_bf16 v[50:53], v[170:173], v[178:181], v[50:53]
	v_mfma_f32_16x16x32_bf16 v[38:41], v[162:165], v[186:189], v[38:41]
	v_mfma_f32_16x16x32_bf16 v[34:37], v[170:173], v[186:189], v[34:37]
	v_mfma_f32_16x16x32_bf16 v[22:25], v[162:165], v[194:197], v[22:25]
	v_mfma_f32_16x16x32_bf16 v[18:21], v[170:173], v[194:197], v[18:21]
	v_mfma_f32_16x16x32_bf16 v[6:9], v[162:165], v[202:205], v[6:9]
	v_mfma_f32_16x16x32_bf16 v[2:5], v[170:173], v[202:205], v[2:5]
	v_mfma_f32_16x16x32_bf16 v[54:57], v[166:169], v[182:185], v[54:57]
	v_mfma_f32_16x16x32_bf16 v[50:53], v[174:177], v[182:185], v[50:53]
	v_mfma_f32_16x16x32_bf16 v[38:41], v[166:169], v[190:193], v[38:41]
	v_mfma_f32_16x16x32_bf16 v[34:37], v[174:177], v[190:193], v[34:37]
	v_mfma_f32_16x16x32_bf16 v[22:25], v[166:169], v[198:201], v[22:25]
	v_mfma_f32_16x16x32_bf16 v[18:21], v[174:177], v[198:201], v[18:21]
	v_mfma_f32_16x16x32_bf16 v[6:9], v[166:169], v[206:209], v[6:9]
	v_mfma_f32_16x16x32_bf16 v[2:5], v[174:177], v[206:209], v[2:5]
	s_setprio 0
	s_barrier
	s_add_i32 s10, s10, 2
	s_addk_i32 s8, 0x100
	s_addk_i32 s9, 0x100
	s_cmp_gt_u32 s10, 61
	s_cbranch_scc0 .LBB0_279
	s_mov_b64 s[10:11], -1
	s_mov_b64 s[4:5], 0
	s_cmp_lt_i32 s18, 1
	s_mov_b64 s[8:9], 0
	v_mbcnt_lo_u32_b32 v0, -1, 0
	v_mbcnt_hi_u32_b32 v0, -1, v0
	s_cbranch_scc1 .LBB0_295
	s_cmp_lg_u32 s18, 1
	s_cselect_b64 s[8:9], -1, 0
	s_cbranch_execz .LBB0_296

; #define LAS __attribute__((address_space(3)))
; #define GAS __attribute__((address_space(1)))
; __device__ __forceinline__ void mem_unit(LAS unsigned char* lds, const bf16_t* Qb, const bf16_t* KVg, const bf16_t* Zb, bf16_t* Ob, int tid) {
;     const int wid = __builtin_amdgcn_readfirstlane(tid >> 6), lane = tid & 63, r32 = lane & 31, hi = lane >> 5;
;     bf16x8 kv[16];
; #pragma unroll
;     for (int i = 0; i < 16; ++i) { const int ch = i * 512 + tid, key = ch >> 5, c16 = ch & 31; kv[i] = *(const GAS bf16x8*)((const GAS bf16_t*)KVg + (size_t)key * KVW + c16 * 8); }
;     __syncthreads();
; #pragma unroll
;     for (int i = 0; i < 16; ++i) { const int ch = i * 512 + tid, key = ch >> 5, c16 = ch & 31; *(LAS bf16x8*)(lds + key * 512 + ((c16 * 16) ^ ((key & 7) << 4))) = kv[i]; }
.LBB0_544:
	s_ashr_i32 s4, s8, 5
	s_ashr_i32 s5, s4, 31
	s_lshl_b64 s[36:37], s[4:5], 11
	s_and_b32 s12, s11, 0x700
	s_or_b32 s36, s36, s12
	v_mad_u64_u32 v[2:3], s[12:13], s36, v126, v[196:197]
	s_mul_i32 s18, s37, 0xc000
	s_and_b32 s12, s9, 0x300
	s_lshl_b64 s[4:5], s[4:5], 20
	v_mbcnt_lo_u32_b32 v100, -1, 0
	v_mbcnt_hi_u32_b32 v100, -1, v100
	v_add_u32_e32 v3, s18, v3
	v_add_u32_e32 v228, s33, v100
	s_lshl_b32 s18, s12, 1
	v_lshl_add_u64 v[4:5], v[198:199], 0, s[4:5]
	v_lshlrev_b32_e32 v231, 4, v228
	v_ashrrev_i32_e32 v68, 5, v228
	v_lshl_add_u64 v[130:131], v[4:5], 0, s[18:19]
	v_and_b32_e32 v0, 0x1f0, v231
	v_ashrrev_i32_e32 v69, 31, v68
	v_lshl_add_u64 v[64:65], v[130:131], 0, v[0:1]
	v_lshlrev_b64 v[132:133], 12, v[68:69]
	v_add_u32_e32 v230, 0x200, v228
	v_lshl_add_u64 v[4:5], v[64:65], 0, v[132:133]
	v_ashrrev_i32_e32 v70, 5, v230
	global_load_dwordx4 v[4:7], v[4:5], off
	v_ashrrev_i32_e32 v71, 31, v70
	v_add_u32_e32 v229, 0x400, v228
	v_lshlrev_b64 v[134:135], 12, v[70:71]
	v_ashrrev_i32_e32 v72, 5, v229
	v_lshl_add_u64 v[8:9], v[64:65], 0, v[134:135]
	v_ashrrev_i32_e32 v73, 31, v72
	v_add_u32_e32 v227, 0x600, v228
	global_load_dwordx4 v[8:11], v[8:9], off
	v_lshlrev_b64 v[136:137], 12, v[72:73]
	v_ashrrev_i32_e32 v74, 5, v227
	v_lshl_add_u64 v[12:13], v[64:65], 0, v[136:137]
	v_ashrrev_i32_e32 v75, 31, v74
	v_add_u32_e32 v226, 0x800, v228
	global_load_dwordx4 v[12:15], v[12:13], off
	v_lshlrev_b64 v[138:139], 12, v[74:75]
	v_ashrrev_i32_e32 v76, 5, v226
	v_lshl_add_u64 v[16:17], v[64:65], 0, v[138:139]
	v_ashrrev_i32_e32 v77, 31, v76
	v_add_u32_e32 v225, 0xa00, v228
	global_load_dwordx4 v[16:19], v[16:17], off
	v_lshlrev_b64 v[140:141], 12, v[76:77]
	v_ashrrev_i32_e32 v78, 5, v225
	v_lshl_add_u64 v[20:21], v[64:65], 0, v[140:141]
	v_ashrrev_i32_e32 v79, 31, v78
	v_add_u32_e32 v224, 0xc00, v228
	global_load_dwordx4 v[20:23], v[20:21], off
	v_lshlrev_b64 v[142:143], 12, v[78:79]
	v_ashrrev_i32_e32 v80, 5, v224
	v_lshl_add_u64 v[24:25], v[64:65], 0, v[142:143]
	v_ashrrev_i32_e32 v81, 31, v80
	v_add_u32_e32 v223, 0xe00, v228
	global_load_dwordx4 v[24:27], v[24:25], off
	v_lshlrev_b64 v[144:145], 12, v[80:81]
	v_ashrrev_i32_e32 v82, 5, v223
	v_lshl_add_u64 v[28:29], v[64:65], 0, v[144:145]
	v_ashrrev_i32_e32 v83, 31, v82
	v_add_u32_e32 v222, 0x1000, v228
	global_load_dwordx4 v[28:31], v[28:29], off
	v_lshlrev_b64 v[146:147], 12, v[82:83]
	v_ashrrev_i32_e32 v84, 5, v222
	v_lshl_add_u64 v[32:33], v[64:65], 0, v[146:147]
	v_ashrrev_i32_e32 v85, 31, v84
	v_add_u32_e32 v221, 0x1200, v228
	global_load_dwordx4 v[32:35], v[32:33], off
	v_lshlrev_b64 v[148:149], 12, v[84:85]
	v_ashrrev_i32_e32 v86, 5, v221
	v_lshl_add_u64 v[36:37], v[64:65], 0, v[148:149]
	v_ashrrev_i32_e32 v87, 31, v86
	v_add_u32_e32 v220, 0x1400, v228
	global_load_dwordx4 v[36:39], v[36:37], off
	v_lshlrev_b64 v[150:151], 12, v[86:87]
	v_ashrrev_i32_e32 v88, 5, v220
	v_lshl_add_u64 v[40:41], v[64:65], 0, v[150:151]
	v_ashrrev_i32_e32 v89, 31, v88
	v_add_u32_e32 v219, 0x1600, v228
	global_load_dwordx4 v[40:43], v[40:41], off
	v_lshlrev_b64 v[152:153], 12, v[88:89]
	v_ashrrev_i32_e32 v90, 5, v219
	v_lshl_add_u64 v[44:45], v[64:65], 0, v[152:153]
	v_ashrrev_i32_e32 v91, 31, v90
	v_add_u32_e32 v218, 0x1800, v228
	global_load_dwordx4 v[44:47], v[44:45], off
	v_lshlrev_b64 v[202:203], 12, v[90:91]
	v_ashrrev_i32_e32 v92, 5, v218
	v_lshl_add_u64 v[48:49], v[64:65], 0, v[202:203]
	v_ashrrev_i32_e32 v93, 31, v92
	v_add_u32_e32 v217, 0x1a00, v228
	global_load_dwordx4 v[48:51], v[48:49], off
	v_lshlrev_b64 v[204:205], 12, v[92:93]
	v_ashrrev_i32_e32 v94, 5, v217
	v_lshl_add_u64 v[52:53], v[64:65], 0, v[204:205]
	v_ashrrev_i32_e32 v95, 31, v94
	v_add_u32_e32 v216, 0x1c00, v228
	global_load_dwordx4 v[52:55], v[52:53], off
	v_lshlrev_b64 v[206:207], 12, v[94:95]
	v_ashrrev_i32_e32 v96, 5, v216
	v_lshl_add_u64 v[56:57], v[64:65], 0, v[206:207]
	v_ashrrev_i32_e32 v97, 31, v96
	v_add_u32_e32 v215, 0x1e00, v228
	global_load_dwordx4 v[56:59], v[56:57], off
	v_lshlrev_b64 v[208:209], 12, v[96:97]
	v_ashrrev_i32_e32 v98, 5, v215
	v_lshl_add_u64 v[60:61], v[64:65], 0, v[208:209]
	v_ashrrev_i32_e32 v99, 31, v98
	global_load_dwordx4 v[60:63], v[60:61], off
	v_lshlrev_b64 v[210:211], 12, v[98:99]
	v_lshl_add_u64 v[64:65], v[64:65], 0, v[210:211]
	global_load_dwordx4 v[64:67], v[64:65], off
	v_lshlrev_b32_e32 v69, 9, v68
	v_lshlrev_b32_e32 v68, 4, v68
	v_bitop3_b32 v68, v68, v0, s94 bitop3:0x6c
	v_add3_u32 v68, 0, v69, v68
	s_barrier
; #define LAS __attribute__((address_space(3)))
; #define GAS __attribute__((address_space(1)))
; __device__ __forceinline__ void mem_unit(LAS unsigned char* lds, const bf16_t* Qb, const bf16_t* KVg, const bf16_t* Zb, bf16_t* Ob, int tid) {
;     ...
;     for (int i = 0; i < 16; ++i) { const int ch = i * 512 + tid, key = ch >> 5, c16 = ch & 31; *(LAS bf16x8*)(lds + key * 512 + ((c16 * 16) ^ ((key & 7) << 4))) = kv[i]; }
;     __syncthreads();
;     f32x16 p[8];
; #pragma unroll
;     for (int kb = 0; kb < 8; ++kb) p[kb] = (f32x16){};
;     const GAS bf16_t* Qw = (const GAS bf16_t*)Qb + (size_t)(wid * 32 + r32) * INW + hi * 8;
; #pragma unroll
;     for (int d0 = 0; d0 < 16; ++d0) { const bf16x8 qf = *(const GAS bf16x8*)(Qw + d0 * 16); const int cb = (d0 * 32 + hi * 16) ^ ((r32 & 7) << 4);
; #pragma unroll
;         for (int kb = 0; kb < 8; ++kb) { const bf16x8 kf = *(const LAS bf16x8*)(lds + (kb * 32 + r32) * 512 + cb); p[kb] = __builtin_amdgcn_mfma_f32_32x32x16_bf16(kf, qf, p[kb], 0, 0, 0); } }
; #pragma unroll
;     for (int i = 0; i < 16; ++i) { const int ch = i * 512 + tid, key = ch >> 5, c16 = ch & 31; kv[i] = *(const GAS bf16x8*)((const GAS bf16_t*)KVg + (size_t)key * KVW + 1024 + c16 * 8); }
	s_waitcnt vmcnt(15)
	ds_write_b128 v68, v[4:7]
	v_lshlrev_b32_e32 v5, 4, v70
	v_lshlrev_b32_e32 v4, 9, v70
	v_bitop3_b32 v5, v5, v0, s94 bitop3:0x6c
	v_add3_u32 v4, 0, v4, v5
	v_lshlrev_b32_e32 v5, 4, v72
	s_waitcnt vmcnt(14)
	ds_write_b128 v4, v[8:11]
	v_lshlrev_b32_e32 v4, 9, v72
	v_bitop3_b32 v5, v5, v0, s94 bitop3:0x6c
	v_add3_u32 v4, 0, v4, v5
	v_lshlrev_b32_e32 v5, 4, v74
	s_waitcnt vmcnt(13)
	ds_write_b128 v4, v[12:15]
	v_lshlrev_b32_e32 v4, 9, v74
	v_bitop3_b32 v5, v5, v0, s94 bitop3:0x6c
	v_add3_u32 v4, 0, v4, v5
	v_lshlrev_b32_e32 v5, 4, v76
	s_waitcnt vmcnt(12)
	ds_write_b128 v4, v[16:19]
	v_lshlrev_b32_e32 v4, 9, v76
	v_bitop3_b32 v5, v5, v0, s94 bitop3:0x6c
	v_add3_u32 v4, 0, v4, v5
	v_lshlrev_b32_e32 v5, 4, v78
	s_waitcnt vmcnt(11)
	ds_write_b128 v4, v[20:23]
	v_lshlrev_b32_e32 v4, 9, v78
	v_bitop3_b32 v5, v5, v0, s94 bitop3:0x6c
	v_add3_u32 v4, 0, v4, v5
	v_lshlrev_b32_e32 v5, 4, v80
	s_waitcnt vmcnt(10)
	ds_write_b128 v4, v[24:27]
	v_lshlrev_b32_e32 v4, 9, v80
	v_bitop3_b32 v5, v5, v0, s94 bitop3:0x6c
	v_add3_u32 v4, 0, v4, v5
	v_lshlrev_b32_e32 v5, 4, v82
	s_waitcnt vmcnt(9)
	ds_write_b128 v4, v[28:31]
	v_lshlrev_b32_e32 v4, 9, v82
	v_bitop3_b32 v5, v5, v0, s94 bitop3:0x6c
	v_add3_u32 v4, 0, v4, v5
	v_lshlrev_b32_e32 v5, 4, v84
	s_waitcnt vmcnt(8)
	ds_write_b128 v4, v[32:35]
	v_lshlrev_b32_e32 v4, 9, v84
	v_bitop3_b32 v5, v5, v0, s94 bitop3:0x6c
	v_add3_u32 v4, 0, v4, v5
	v_lshlrev_b32_e32 v5, 4, v86
	s_waitcnt vmcnt(7)
	ds_write_b128 v4, v[36:39]
	v_lshlrev_b32_e32 v4, 9, v86
	v_bitop3_b32 v5, v5, v0, s94 bitop3:0x6c
	v_add3_u32 v4, 0, v4, v5
	v_lshlrev_b32_e32 v5, 4, v88
	s_waitcnt vmcnt(6)
	ds_write_b128 v4, v[40:43]
	v_lshlrev_b32_e32 v4, 9, v88
	v_bitop3_b32 v5, v5, v0, s94 bitop3:0x6c
	v_add3_u32 v4, 0, v4, v5
	v_lshlrev_b32_e32 v5, 4, v90
	s_waitcnt vmcnt(5)
	ds_write_b128 v4, v[44:47]
	v_lshlrev_b32_e32 v4, 9, v90
	v_bitop3_b32 v5, v5, v0, s94 bitop3:0x6c
	v_add3_u32 v4, 0, v4, v5
	v_lshlrev_b32_e32 v5, 4, v92
	s_waitcnt vmcnt(4)
	ds_write_b128 v4, v[48:51]
	v_lshlrev_b32_e32 v4, 9, v92
	v_bitop3_b32 v5, v5, v0, s94 bitop3:0x6c
	v_add3_u32 v4, 0, v4, v5
	v_lshlrev_b32_e32 v5, 4, v94
	s_waitcnt vmcnt(3)
	ds_write_b128 v4, v[52:55]
	v_lshlrev_b32_e32 v4, 9, v94
	v_bitop3_b32 v5, v5, v0, s94 bitop3:0x6c
	v_add3_u32 v4, 0, v4, v5
	v_lshlrev_b32_e32 v5, 4, v96
	s_waitcnt vmcnt(2)
	ds_write_b128 v4, v[56:59]
	v_lshlrev_b32_e32 v4, 9, v96
	v_bitop3_b32 v5, v5, v0, s94 bitop3:0x6c
	v_readfirstlane_b32 s4, v228
	v_add3_u32 v4, 0, v4, v5
	v_lshlrev_b32_e32 v5, 4, v98
	s_ashr_i32 s23, s4, 6
	s_waitcnt vmcnt(1)
	ds_write_b128 v4, v[60:63]
	v_lshlrev_b32_e32 v4, 9, v98
	v_bitop3_b32 v5, v5, v0, s94 bitop3:0x6c
	v_lshl_add_u64 v[200:201], v[2:3], 0, s[18:19]
	s_mov_b64 s[12:13], 0x5000
	v_and_b32_e32 v214, 31, v100
	v_add3_u32 v4, 0, v4, v5
	s_lshl_b32 s86, s23, 5
	v_lshl_add_u64 v[2:3], v[200:201], 0, s[12:13]
	s_waitcnt vmcnt(0)
	ds_write_b128 v4, v[64:67]
	v_bfe_u32 v213, v100, 5, 1
	v_or_b32_e32 v4, s86, v214
	v_mad_i64_i32 v[2:3], s[4:5], v4, s93, v[2:3]
	v_lshlrev_b32_e32 v154, 4, v213
	v_mov_b32_e32 v155, v1
	v_lshl_add_u64 v[156:157], v[2:3], 0, v[154:155]
	s_waitcnt lgkmcnt(0)
	s_barrier
	global_load_dwordx4 v[2:5], v[156:157], off
	global_load_dwordx4 v[160:163], v[156:157], off offset:32
	global_load_dwordx4 v[232:235], v[156:157], off offset:64
	global_load_dwordx4 v[236:239], v[156:157], off offset:96
	global_load_dwordx4 v[240:243], v[156:157], off offset:128
	global_load_dwordx4 v[246:249], v[156:157], off offset:160
	v_and_b32_e32 v155, 0x70, v231
	v_lshl_add_u32 v158, v214, 9, 0
	v_xad_u32 v10, v154, v155, v158
	ds_read_b128 v[6:9], v10
	v_lshl_add_u64 v[132:133], v[130:131], 0, v[132:133]
	v_lshl_add_u64 v[132:133], v[132:133], 0, v[0:1]
	global_load_dwordx4 v[190:193], v[132:133], off offset:2048
	s_waitcnt vmcnt(6) lgkmcnt(0)
	v_mfma_f32_32x32x16_bf16 v[114:129], v[6:9], v[2:5], 0
	ds_read_b128 v[6:9], v10 offset:16384
	v_and_b32_e32 v212, 63, v100
	v_or_b32_e32 v159, 32, v154
	v_xad_u32 v159, v159, v155, v158
	ds_read_b128 v[164:167], v159
	v_lshl_add_u64 v[132:133], v[130:131], 0, v[134:135]
	v_lshl_add_u64 v[132:133], v[132:133], 0, v[0:1]
	s_waitcnt lgkmcnt(1)
	v_mfma_f32_32x32x16_bf16 v[98:113], v[6:9], v[2:5], 0
	ds_read_b128 v[6:9], v10 offset:32768
	global_load_dwordx4 v[186:189], v[132:133], off offset:2048
	v_lshl_add_u64 v[132:133], v[130:131], 0, v[136:137]
	v_lshl_add_u64 v[132:133], v[132:133], 0, v[0:1]
	global_load_dwordx4 v[182:185], v[132:133], off offset:2048
	v_lshl_add_u64 v[132:133], v[130:131], 0, v[138:139]
	v_lshl_add_u64 v[132:133], v[132:133], 0, v[0:1]
	s_waitcnt lgkmcnt(0)
	v_mfma_f32_32x32x16_bf16 v[82:97], v[6:9], v[2:5], 0
	ds_read_b128 v[6:9], v10 offset:49152
	s_lshl_b32 s4, s23, 7
	s_add_i32 s12, s4, 0
	s_add_i32 s12, s12, 0x20400
	v_cmp_gt_u32_e32 vcc, 32, v212
	global_load_dwordx4 v[178:181], v[132:133], off offset:2048
	v_lshl_add_u64 v[132:133], v[130:131], 0, v[140:141]
	s_waitcnt vmcnt(8)
	v_mfma_f32_32x32x16_bf16 v[114:129], v[164:167], v[160:163], v[114:129]
	ds_read_b128 v[164:167], v159 offset:16384
	v_lshl_add_u64 v[132:133], v[132:133], 0, v[0:1]
	global_load_dwordx4 v[174:177], v[132:133], off offset:2048
	v_lshl_add_u64 v[132:133], v[130:131], 0, v[142:143]
	v_lshl_add_u64 v[132:133], v[132:133], 0, v[0:1]
	global_load_dwordx4 v[170:173], v[132:133], off offset:2048
	v_lshl_add_u64 v[132:133], v[130:131], 0, v[144:145]
	s_waitcnt lgkmcnt(1)
	v_mfma_f32_32x32x16_bf16 v[66:81], v[6:9], v[2:5], 0
	v_add_u32_e32 v6, 0x10000, v10
	ds_read_b128 v[6:9], v6
	v_lshl_add_u64 v[132:133], v[132:133], 0, v[0:1]
	s_waitcnt lgkmcnt(1)
; #define LAS __attribute__((address_space(3)))
; #define GAS __attribute__((address_space(1)))
; __device__ __forceinline__ void mem_unit(LAS unsigned char* lds, const bf16_t* Qb, const bf16_t* KVg, const bf16_t* Zb, bf16_t* Ob, int tid) {
;     ...
;     for (int d0 = 0; d0 < 16; ++d0) { const bf16x8 qf = *(const GAS bf16x8*)(Qw + d0 * 16); const int cb = (d0 * 32 + hi * 16) ^ ((r32 & 7) << 4);
; #pragma unroll
;         for (int kb = 0; kb < 8; ++kb) { const bf16x8 kf = *(const LAS bf16x8*)(lds + (kb * 32 + r32) * 512 + cb); p[kb] = __builtin_amdgcn_mfma_f32_32x32x16_bf16(kf, qf, p[kb], 0, 0, 0); } }
;     ...
;     for (int i = 0; i < 16; ++i) { const int ch = i * 512 + tid, key = ch >> 5, c16 = ch & 31; kv[i] = *(const GAS bf16x8*)((const GAS bf16_t*)KVg + (size_t)key * KVW + 1024 + c16 * 8); }
	v_mfma_f32_32x32x16_bf16 v[98:113], v[164:167], v[160:163], v[98:113]
	ds_read_b128 v[164:167], v159 offset:32768
	s_waitcnt lgkmcnt(1)
	v_mfma_f32_32x32x16_bf16 v[50:65], v[6:9], v[2:5], 0
	v_add_u32_e32 v6, 0x14000, v10
	ds_read_b128 v[6:9], v6
	s_waitcnt lgkmcnt(1)
	v_mfma_f32_32x32x16_bf16 v[82:97], v[164:167], v[160:163], v[82:97]
	ds_read_b128 v[164:167], v159 offset:49152
	s_waitcnt lgkmcnt(1)
	v_mfma_f32_32x32x16_bf16 v[34:49], v[6:9], v[2:5], 0
	v_add_u32_e32 v6, 0x18000, v10
	ds_read_b128 v[6:9], v6
	s_waitcnt lgkmcnt(1)
	v_mfma_f32_32x32x16_bf16 v[66:81], v[164:167], v[160:163], v[66:81]
	v_add_u32_e32 v164, 0x10000, v159
	ds_read_b128 v[164:167], v164
	s_waitcnt lgkmcnt(0)
	v_mfma_f32_32x32x16_bf16 v[50:65], v[164:167], v[160:163], v[50:65]
	v_add_u32_e32 v164, 0x14000, v159
	ds_read_b128 v[164:167], v164
	s_waitcnt lgkmcnt(0)
	v_mfma_f32_32x32x16_bf16 v[34:49], v[164:167], v[160:163], v[34:49]
	v_add_u32_e32 v164, 0x18000, v159
	ds_read_b128 v[164:167], v164
	v_add_u32_e32 v159, 0x1c000, v159
	v_mfma_f32_32x32x16_bf16 v[18:33], v[6:9], v[2:5], 0
	v_add_u32_e32 v6, 0x1c000, v10
	ds_read_b128 v[6:9], v6
	s_waitcnt lgkmcnt(1)
	v_mfma_f32_32x32x16_bf16 v[18:33], v[164:167], v[160:163], v[18:33]
	ds_read_b128 v[164:167], v159
	v_or_b32_e32 v159, 64, v154
	v_xad_u32 v159, v159, v155, v158
	s_waitcnt lgkmcnt(1)
	v_mfma_f32_32x32x16_bf16 v[2:17], v[6:9], v[2:5], 0
	s_waitcnt lgkmcnt(0)
	v_mfma_f32_32x32x16_bf16 v[2:17], v[164:167], v[160:163], v[2:17]
	ds_read_b128 v[164:167], v159
	s_waitcnt vmcnt(9) lgkmcnt(0)
	v_mfma_f32_32x32x16_bf16 v[114:129], v[164:167], v[232:235], v[114:129]
	ds_read_b128 v[164:167], v159 offset:16384
	s_waitcnt lgkmcnt(0)
	v_mfma_f32_32x32x16_bf16 v[98:113], v[164:167], v[232:235], v[98:113]
	ds_read_b128 v[164:167], v159 offset:32768
	s_waitcnt lgkmcnt(0)
	v_mfma_f32_32x32x16_bf16 v[82:97], v[164:167], v[232:235], v[82:97]
	ds_read_b128 v[164:167], v159 offset:49152
	s_waitcnt lgkmcnt(0)
	v_mfma_f32_32x32x16_bf16 v[66:81], v[164:167], v[232:235], v[66:81]
	v_add_u32_e32 v164, 0x10000, v159
	ds_read_b128 v[164:167], v164
	s_waitcnt lgkmcnt(0)
	v_mfma_f32_32x32x16_bf16 v[50:65], v[164:167], v[232:235], v[50:65]
	v_add_u32_e32 v164, 0x14000, v159
	ds_read_b128 v[164:167], v164
	s_waitcnt lgkmcnt(0)
	v_mfma_f32_32x32x16_bf16 v[34:49], v[164:167], v[232:235], v[34:49]
	v_add_u32_e32 v164, 0x18000, v159
	ds_read_b128 v[164:167], v164
	v_add_u32_e32 v159, 0x1c000, v159
	s_waitcnt lgkmcnt(0)
	v_mfma_f32_32x32x16_bf16 v[18:33], v[164:167], v[232:235], v[18:33]
	ds_read_b128 v[164:167], v159
	v_or_b32_e32 v159, 0x60, v154
	v_xad_u32 v159, v159, v155, v158
	s_waitcnt lgkmcnt(0)
	v_mfma_f32_32x32x16_bf16 v[2:17], v[164:167], v[232:235], v[2:17]
	global_load_dwordx4 v[232:235], v[156:157], off offset:192
	ds_read_b128 v[164:167], v159
	s_waitcnt vmcnt(9) lgkmcnt(0)
	v_mfma_f32_32x32x16_bf16 v[114:129], v[164:167], v[236:239], v[114:129]
	ds_read_b128 v[164:167], v159 offset:16384
	s_waitcnt lgkmcnt(0)
	v_mfma_f32_32x32x16_bf16 v[98:113], v[164:167], v[236:239], v[98:113]
	ds_read_b128 v[164:167], v159 offset:32768
	s_waitcnt lgkmcnt(0)
	v_mfma_f32_32x32x16_bf16 v[82:97], v[164:167], v[236:239], v[82:97]
	ds_read_b128 v[164:167], v159 offset:49152
	s_waitcnt lgkmcnt(0)
	v_mfma_f32_32x32x16_bf16 v[66:81], v[164:167], v[236:239], v[66:81]
	v_add_u32_e32 v164, 0x10000, v159
	ds_read_b128 v[164:167], v164
	s_waitcnt lgkmcnt(0)
	v_mfma_f32_32x32x16_bf16 v[50:65], v[164:167], v[236:239], v[50:65]
	v_add_u32_e32 v164, 0x14000, v159
	ds_read_b128 v[164:167], v164
	s_waitcnt lgkmcnt(0)
	v_mfma_f32_32x32x16_bf16 v[34:49], v[164:167], v[236:239], v[34:49]
	v_add_u32_e32 v164, 0x18000, v159
	ds_read_b128 v[164:167], v164
	v_add_u32_e32 v159, 0x1c000, v159
	s_waitcnt lgkmcnt(0)
	v_mfma_f32_32x32x16_bf16 v[18:33], v[164:167], v[236:239], v[18:33]
	ds_read_b128 v[164:167], v159
	v_or_b32_e32 v159, 0x80, v154
	v_xad_u32 v159, v159, v155, v158
	s_waitcnt lgkmcnt(0)
	v_mfma_f32_32x32x16_bf16 v[2:17], v[164:167], v[236:239], v[2:17]
	global_load_dwordx4 v[236:239], v[156:157], off offset:224
	ds_read_b128 v[164:167], v159
	s_waitcnt vmcnt(9) lgkmcnt(0)
	v_mfma_f32_32x32x16_bf16 v[114:129], v[164:167], v[240:243], v[114:129]
	ds_read_b128 v[164:167], v159 offset:16384
	s_waitcnt lgkmcnt(0)
	v_mfma_f32_32x32x16_bf16 v[98:113], v[164:167], v[240:243], v[98:113]
	ds_read_b128 v[164:167], v159 offset:32768
	s_waitcnt lgkmcnt(0)
	v_mfma_f32_32x32x16_bf16 v[82:97], v[164:167], v[240:243], v[82:97]
	ds_read_b128 v[164:167], v159 offset:49152
	s_waitcnt lgkmcnt(0)
	v_mfma_f32_32x32x16_bf16 v[66:81], v[164:167], v[240:243], v[66:81]
	v_add_u32_e32 v164, 0x10000, v159
	ds_read_b128 v[164:167], v164
	s_waitcnt lgkmcnt(0)
	v_mfma_f32_32x32x16_bf16 v[50:65], v[164:167], v[240:243], v[50:65]
	v_add_u32_e32 v164, 0x14000, v159
	ds_read_b128 v[164:167], v164
	s_waitcnt lgkmcnt(0)
	v_mfma_f32_32x32x16_bf16 v[34:49], v[164:167], v[240:243], v[34:49]
	v_add_u32_e32 v164, 0x18000, v159
	ds_read_b128 v[164:167], v164
	v_add_u32_e32 v159, 0x1c000, v159
	s_waitcnt lgkmcnt(0)
	v_mfma_f32_32x32x16_bf16 v[18:33], v[164:167], v[240:243], v[18:33]
	ds_read_b128 v[164:167], v159
	v_or_b32_e32 v159, 0xa0, v154
	v_xad_u32 v159, v159, v155, v158
	s_waitcnt lgkmcnt(0)
	v_mfma_f32_32x32x16_bf16 v[2:17], v[164:167], v[240:243], v[2:17]
	global_load_dwordx4 v[240:243], v[156:157], off offset:256
	ds_read_b128 v[164:167], v159
	s_waitcnt vmcnt(9) lgkmcnt(0)
	v_mfma_f32_32x32x16_bf16 v[114:129], v[164:167], v[246:249], v[114:129]
	ds_read_b128 v[164:167], v159 offset:16384
	s_waitcnt lgkmcnt(0)
	v_mfma_f32_32x32x16_bf16 v[98:113], v[164:167], v[246:249], v[98:113]
	ds_read_b128 v[164:167], v159 offset:32768
	s_waitcnt lgkmcnt(0)
; #define LAS __attribute__((address_space(3)))
; #define GAS __attribute__((address_space(1)))
; __device__ __forceinline__ void mem_unit(LAS unsigned char* lds, const bf16_t* Qb, const bf16_t* KVg, const bf16_t* Zb, bf16_t* Ob, int tid) {
;     ...
;     for (int d0 = 0; d0 < 16; ++d0) { const bf16x8 qf = *(const GAS bf16x8*)(Qw + d0 * 16); const int cb = (d0 * 32 + hi * 16) ^ ((r32 & 7) << 4);
; #pragma unroll
;         for (int kb = 0; kb < 8; ++kb) { const bf16x8 kf = *(const LAS bf16x8*)(lds + (kb * 32 + r32) * 512 + cb); p[kb] = __builtin_amdgcn_mfma_f32_32x32x16_bf16(kf, qf, p[kb], 0, 0, 0); } }
	v_mfma_f32_32x32x16_bf16 v[82:97], v[164:167], v[246:249], v[82:97]
	ds_read_b128 v[164:167], v159 offset:49152
	s_waitcnt lgkmcnt(0)
	v_mfma_f32_32x32x16_bf16 v[66:81], v[164:167], v[246:249], v[66:81]
	v_add_u32_e32 v164, 0x10000, v159
	ds_read_b128 v[164:167], v164
	s_waitcnt lgkmcnt(0)
	v_mfma_f32_32x32x16_bf16 v[50:65], v[164:167], v[246:249], v[50:65]
	v_add_u32_e32 v164, 0x14000, v159
	ds_read_b128 v[164:167], v164
	s_waitcnt lgkmcnt(0)
	v_mfma_f32_32x32x16_bf16 v[34:49], v[164:167], v[246:249], v[34:49]
	v_add_u32_e32 v164, 0x18000, v159
	ds_read_b128 v[164:167], v164
	v_add_u32_e32 v159, 0x1c000, v159
	s_waitcnt lgkmcnt(0)
	v_mfma_f32_32x32x16_bf16 v[18:33], v[164:167], v[246:249], v[18:33]
	ds_read_b128 v[164:167], v159
	v_or_b32_e32 v159, 0xc0, v154
	v_xad_u32 v159, v159, v155, v158
	s_waitcnt lgkmcnt(0)
	v_mfma_f32_32x32x16_bf16 v[2:17], v[164:167], v[246:249], v[2:17]
	global_load_dwordx4 v[246:249], v[156:157], off offset:288
	ds_read_b128 v[164:167], v159
	s_waitcnt vmcnt(3) lgkmcnt(0)
	v_mfma_f32_32x32x16_bf16 v[114:129], v[164:167], v[232:235], v[114:129]
	ds_read_b128 v[164:167], v159 offset:16384
	s_waitcnt lgkmcnt(0)
	v_mfma_f32_32x32x16_bf16 v[98:113], v[164:167], v[232:235], v[98:113]
	ds_read_b128 v[164:167], v159 offset:32768
	s_waitcnt lgkmcnt(0)
	v_mfma_f32_32x32x16_bf16 v[82:97], v[164:167], v[232:235], v[82:97]
	ds_read_b128 v[164:167], v159 offset:49152
	s_waitcnt lgkmcnt(0)
	v_mfma_f32_32x32x16_bf16 v[66:81], v[164:167], v[232:235], v[66:81]
	v_add_u32_e32 v164, 0x10000, v159
	ds_read_b128 v[164:167], v164
	s_waitcnt lgkmcnt(0)
	v_mfma_f32_32x32x16_bf16 v[50:65], v[164:167], v[232:235], v[50:65]
	v_add_u32_e32 v164, 0x14000, v159
	ds_read_b128 v[164:167], v164
	s_waitcnt lgkmcnt(0)
	v_mfma_f32_32x32x16_bf16 v[34:49], v[164:167], v[232:235], v[34:49]
	v_add_u32_e32 v164, 0x18000, v159
	ds_read_b128 v[164:167], v164
	v_add_u32_e32 v159, 0x1c000, v159
	s_waitcnt lgkmcnt(0)
	v_mfma_f32_32x32x16_bf16 v[18:33], v[164:167], v[232:235], v[18:33]
	ds_read_b128 v[164:167], v159
	v_or_b32_e32 v159, 0xe0, v154
	v_xad_u32 v159, v159, v155, v158
	s_waitcnt lgkmcnt(0)
	v_mfma_f32_32x32x16_bf16 v[2:17], v[164:167], v[232:235], v[2:17]
	global_load_dwordx4 v[232:235], v[156:157], off offset:320
	ds_read_b128 v[164:167], v159
	s_waitcnt vmcnt(3) lgkmcnt(0)
	v_mfma_f32_32x32x16_bf16 v[114:129], v[164:167], v[236:239], v[114:129]
	ds_read_b128 v[164:167], v159 offset:16384
	s_waitcnt lgkmcnt(0)
	v_mfma_f32_32x32x16_bf16 v[98:113], v[164:167], v[236:239], v[98:113]
	ds_read_b128 v[164:167], v159 offset:32768
	s_waitcnt lgkmcnt(0)
	v_mfma_f32_32x32x16_bf16 v[82:97], v[164:167], v[236:239], v[82:97]
	ds_read_b128 v[164:167], v159 offset:49152
	s_waitcnt lgkmcnt(0)
	v_mfma_f32_32x32x16_bf16 v[66:81], v[164:167], v[236:239], v[66:81]
	v_add_u32_e32 v164, 0x10000, v159
	ds_read_b128 v[164:167], v164
	s_waitcnt lgkmcnt(0)
	v_mfma_f32_32x32x16_bf16 v[50:65], v[164:167], v[236:239], v[50:65]
	v_add_u32_e32 v164, 0x14000, v159
	ds_read_b128 v[164:167], v164
	s_waitcnt lgkmcnt(0)
	v_mfma_f32_32x32x16_bf16 v[34:49], v[164:167], v[236:239], v[34:49]
	v_add_u32_e32 v164, 0x18000, v159
	ds_read_b128 v[164:167], v164
	v_add_u32_e32 v159, 0x1c000, v159
	s_waitcnt lgkmcnt(0)
	v_mfma_f32_32x32x16_bf16 v[18:33], v[164:167], v[236:239], v[18:33]
	ds_read_b128 v[164:167], v159
	v_or_b32_e32 v159, 0x100, v154
	v_xad_u32 v159, v159, v155, v158
	s_waitcnt lgkmcnt(0)
	v_mfma_f32_32x32x16_bf16 v[2:17], v[164:167], v[236:239], v[2:17]
	global_load_dwordx4 v[236:239], v[156:157], off offset:352
	ds_read_b128 v[164:167], v159
	s_waitcnt vmcnt(3) lgkmcnt(0)
	v_mfma_f32_32x32x16_bf16 v[114:129], v[164:167], v[240:243], v[114:129]
	ds_read_b128 v[164:167], v159 offset:16384
	s_waitcnt lgkmcnt(0)
	v_mfma_f32_32x32x16_bf16 v[98:113], v[164:167], v[240:243], v[98:113]
	ds_read_b128 v[164:167], v159 offset:32768
	s_waitcnt lgkmcnt(0)
	v_mfma_f32_32x32x16_bf16 v[82:97], v[164:167], v[240:243], v[82:97]
	ds_read_b128 v[164:167], v159 offset:49152
	s_waitcnt lgkmcnt(0)
	v_mfma_f32_32x32x16_bf16 v[66:81], v[164:167], v[240:243], v[66:81]
	v_add_u32_e32 v164, 0x10000, v159
	ds_read_b128 v[164:167], v164
	s_waitcnt lgkmcnt(0)
	v_mfma_f32_32x32x16_bf16 v[50:65], v[164:167], v[240:243], v[50:65]
	v_add_u32_e32 v164, 0x14000, v159
	ds_read_b128 v[164:167], v164
	s_waitcnt lgkmcnt(0)
	v_mfma_f32_32x32x16_bf16 v[34:49], v[164:167], v[240:243], v[34:49]
	v_add_u32_e32 v164, 0x18000, v159
	ds_read_b128 v[164:167], v164
	v_add_u32_e32 v159, 0x1c000, v159
	s_waitcnt lgkmcnt(0)
	v_mfma_f32_32x32x16_bf16 v[18:33], v[164:167], v[240:243], v[18:33]
	ds_read_b128 v[164:167], v159
	v_or_b32_e32 v159, 0x120, v154
	v_xad_u32 v159, v159, v155, v158
	s_waitcnt lgkmcnt(0)
	v_mfma_f32_32x32x16_bf16 v[2:17], v[164:167], v[240:243], v[2:17]
	global_load_dwordx4 v[240:243], v[156:157], off offset:384
	ds_read_b128 v[164:167], v159
	s_waitcnt vmcnt(3) lgkmcnt(0)
	v_mfma_f32_32x32x16_bf16 v[114:129], v[164:167], v[246:249], v[114:129]
	ds_read_b128 v[164:167], v159 offset:16384
	s_waitcnt lgkmcnt(0)
	v_mfma_f32_32x32x16_bf16 v[98:113], v[164:167], v[246:249], v[98:113]
	ds_read_b128 v[164:167], v159 offset:32768
	s_waitcnt lgkmcnt(0)
	v_mfma_f32_32x32x16_bf16 v[82:97], v[164:167], v[246:249], v[82:97]
	ds_read_b128 v[164:167], v159 offset:49152
	s_waitcnt lgkmcnt(0)
	v_mfma_f32_32x32x16_bf16 v[66:81], v[164:167], v[246:249], v[66:81]
	v_add_u32_e32 v164, 0x10000, v159
	ds_read_b128 v[164:167], v164
	s_waitcnt lgkmcnt(0)
	v_mfma_f32_32x32x16_bf16 v[50:65], v[164:167], v[246:249], v[50:65]
	v_add_u32_e32 v164, 0x14000, v159
	ds_read_b128 v[164:167], v164
	s_waitcnt lgkmcnt(0)
; #define LAS __attribute__((address_space(3)))
; #define GAS __attribute__((address_space(1)))
; __device__ __forceinline__ void mem_unit(LAS unsigned char* lds, const bf16_t* Qb, const bf16_t* KVg, const bf16_t* Zb, bf16_t* Ob, int tid) {
;     ...
;     for (int d0 = 0; d0 < 16; ++d0) { const bf16x8 qf = *(const GAS bf16x8*)(Qw + d0 * 16); const int cb = (d0 * 32 + hi * 16) ^ ((r32 & 7) << 4);
; #pragma unroll
;         for (int kb = 0; kb < 8; ++kb) { const bf16x8 kf = *(const LAS bf16x8*)(lds + (kb * 32 + r32) * 512 + cb); p[kb] = __builtin_amdgcn_mfma_f32_32x32x16_bf16(kf, qf, p[kb], 0, 0, 0); } }
	v_mfma_f32_32x32x16_bf16 v[34:49], v[164:167], v[246:249], v[34:49]
	v_add_u32_e32 v164, 0x18000, v159
	ds_read_b128 v[164:167], v164
	v_add_u32_e32 v159, 0x1c000, v159
	s_waitcnt lgkmcnt(0)
	v_mfma_f32_32x32x16_bf16 v[18:33], v[164:167], v[246:249], v[18:33]
	ds_read_b128 v[164:167], v159
	v_or_b32_e32 v159, 0x140, v154
	v_xad_u32 v159, v159, v155, v158
	s_waitcnt lgkmcnt(0)
	v_mfma_f32_32x32x16_bf16 v[2:17], v[164:167], v[246:249], v[2:17]
	global_load_dwordx4 v[246:249], v[156:157], off offset:416
	ds_read_b128 v[164:167], v159
	s_waitcnt vmcnt(3) lgkmcnt(0)
	v_mfma_f32_32x32x16_bf16 v[114:129], v[164:167], v[232:235], v[114:129]
	ds_read_b128 v[164:167], v159 offset:16384
	s_waitcnt lgkmcnt(0)
	v_mfma_f32_32x32x16_bf16 v[98:113], v[164:167], v[232:235], v[98:113]
	ds_read_b128 v[164:167], v159 offset:32768
	s_waitcnt lgkmcnt(0)
	v_mfma_f32_32x32x16_bf16 v[82:97], v[164:167], v[232:235], v[82:97]
	ds_read_b128 v[164:167], v159 offset:49152
	s_waitcnt lgkmcnt(0)
	v_mfma_f32_32x32x16_bf16 v[66:81], v[164:167], v[232:235], v[66:81]
	v_add_u32_e32 v164, 0x10000, v159
	ds_read_b128 v[164:167], v164
	s_waitcnt lgkmcnt(0)
	v_mfma_f32_32x32x16_bf16 v[50:65], v[164:167], v[232:235], v[50:65]
	v_add_u32_e32 v164, 0x14000, v159
	ds_read_b128 v[164:167], v164
	s_waitcnt lgkmcnt(0)
	v_mfma_f32_32x32x16_bf16 v[34:49], v[164:167], v[232:235], v[34:49]
	v_add_u32_e32 v164, 0x18000, v159
	ds_read_b128 v[164:167], v164
	v_add_u32_e32 v159, 0x1c000, v159
	s_waitcnt lgkmcnt(0)
	v_mfma_f32_32x32x16_bf16 v[18:33], v[164:167], v[232:235], v[18:33]
	ds_read_b128 v[164:167], v159
	v_or_b32_e32 v159, 0x160, v154
	v_xad_u32 v159, v159, v155, v158
	s_waitcnt lgkmcnt(0)
	v_mfma_f32_32x32x16_bf16 v[2:17], v[164:167], v[232:235], v[2:17]
	global_load_dwordx4 v[232:235], v[156:157], off offset:448
	ds_read_b128 v[164:167], v159
	s_waitcnt vmcnt(3) lgkmcnt(0)
	v_mfma_f32_32x32x16_bf16 v[114:129], v[164:167], v[236:239], v[114:129]
	ds_read_b128 v[164:167], v159 offset:16384
	s_waitcnt lgkmcnt(0)
	v_mfma_f32_32x32x16_bf16 v[98:113], v[164:167], v[236:239], v[98:113]
	ds_read_b128 v[164:167], v159 offset:32768
	s_waitcnt lgkmcnt(0)
	v_mfma_f32_32x32x16_bf16 v[82:97], v[164:167], v[236:239], v[82:97]
	ds_read_b128 v[164:167], v159 offset:49152
	s_waitcnt lgkmcnt(0)
	v_mfma_f32_32x32x16_bf16 v[66:81], v[164:167], v[236:239], v[66:81]
	v_add_u32_e32 v164, 0x10000, v159
	ds_read_b128 v[164:167], v164
	s_waitcnt lgkmcnt(0)
	v_mfma_f32_32x32x16_bf16 v[50:65], v[164:167], v[236:239], v[50:65]
	v_add_u32_e32 v164, 0x14000, v159
	ds_read_b128 v[164:167], v164
	s_waitcnt lgkmcnt(0)
	v_mfma_f32_32x32x16_bf16 v[34:49], v[164:167], v[236:239], v[34:49]
	v_add_u32_e32 v164, 0x18000, v159
	ds_read_b128 v[164:167], v164
	v_add_u32_e32 v159, 0x1c000, v159
	s_waitcnt lgkmcnt(0)
	v_mfma_f32_32x32x16_bf16 v[18:33], v[164:167], v[236:239], v[18:33]
	ds_read_b128 v[164:167], v159
	v_or_b32_e32 v159, 0x180, v154
	v_xad_u32 v159, v159, v155, v158
	s_waitcnt lgkmcnt(0)
	v_mfma_f32_32x32x16_bf16 v[2:17], v[164:167], v[236:239], v[2:17]
	global_load_dwordx4 v[236:239], v[156:157], off offset:480
	ds_read_b128 v[164:167], v159
	s_waitcnt vmcnt(3) lgkmcnt(0)
	v_mfma_f32_32x32x16_bf16 v[114:129], v[164:167], v[240:243], v[114:129]
	ds_read_b128 v[164:167], v159 offset:16384
	s_waitcnt lgkmcnt(0)
	v_mfma_f32_32x32x16_bf16 v[98:113], v[164:167], v[240:243], v[98:113]
	ds_read_b128 v[164:167], v159 offset:32768
	s_waitcnt lgkmcnt(0)
	v_mfma_f32_32x32x16_bf16 v[82:97], v[164:167], v[240:243], v[82:97]
	ds_read_b128 v[164:167], v159 offset:49152
	s_waitcnt lgkmcnt(0)
	v_mfma_f32_32x32x16_bf16 v[66:81], v[164:167], v[240:243], v[66:81]
	v_add_u32_e32 v164, 0x10000, v159
	ds_read_b128 v[164:167], v164
	s_waitcnt lgkmcnt(0)
	v_mfma_f32_32x32x16_bf16 v[50:65], v[164:167], v[240:243], v[50:65]
	v_add_u32_e32 v164, 0x14000, v159
	ds_read_b128 v[164:167], v164
	s_waitcnt lgkmcnt(0)
	v_mfma_f32_32x32x16_bf16 v[34:49], v[164:167], v[240:243], v[34:49]
	v_add_u32_e32 v164, 0x18000, v159
	ds_read_b128 v[164:167], v164
	v_add_u32_e32 v159, 0x1c000, v159
	s_waitcnt lgkmcnt(0)
	v_mfma_f32_32x32x16_bf16 v[18:33], v[164:167], v[240:243], v[18:33]
	ds_read_b128 v[164:167], v159
	v_or_b32_e32 v159, 0x1a0, v154
	v_xad_u32 v159, v159, v155, v158
	s_waitcnt lgkmcnt(0)
	v_mfma_f32_32x32x16_bf16 v[2:17], v[164:167], v[240:243], v[2:17]
	ds_read_b128 v[164:167], v159
	s_waitcnt vmcnt(2) lgkmcnt(0)
	v_mfma_f32_32x32x16_bf16 v[114:129], v[164:167], v[246:249], v[114:129]
	ds_read_b128 v[164:167], v159 offset:16384
	s_waitcnt lgkmcnt(0)
	v_mfma_f32_32x32x16_bf16 v[98:113], v[164:167], v[246:249], v[98:113]
	ds_read_b128 v[164:167], v159 offset:32768
	s_waitcnt lgkmcnt(0)
	v_mfma_f32_32x32x16_bf16 v[82:97], v[164:167], v[246:249], v[82:97]
	ds_read_b128 v[164:167], v159 offset:49152
	s_waitcnt lgkmcnt(0)
	v_mfma_f32_32x32x16_bf16 v[66:81], v[164:167], v[246:249], v[66:81]
	v_add_u32_e32 v164, 0x10000, v159
	ds_read_b128 v[164:167], v164
	s_waitcnt lgkmcnt(0)
	v_mfma_f32_32x32x16_bf16 v[50:65], v[164:167], v[246:249], v[50:65]
	v_add_u32_e32 v164, 0x14000, v159
	ds_read_b128 v[164:167], v164
	s_waitcnt lgkmcnt(0)
	v_mfma_f32_32x32x16_bf16 v[34:49], v[164:167], v[246:249], v[34:49]
	v_add_u32_e32 v164, 0x18000, v159
	ds_read_b128 v[164:167], v164
	v_add_u32_e32 v159, 0x1c000, v159
	s_waitcnt lgkmcnt(0)
	v_mfma_f32_32x32x16_bf16 v[18:33], v[164:167], v[246:249], v[18:33]
	ds_read_b128 v[164:167], v159
	v_or_b32_e32 v159, 0x1c0, v154
	v_xad_u32 v159, v159, v155, v158
	v_or_b32_e32 v154, 0x1e0, v154
	v_xad_u32 v158, v154, v155, v158
	s_waitcnt lgkmcnt(0)
	v_mfma_f32_32x32x16_bf16 v[2:17], v[164:167], v[246:249], v[2:17]
	ds_read_b128 v[164:167], v159
	s_waitcnt vmcnt(1) lgkmcnt(0)
; #define LAS __attribute__((address_space(3)))
; #define GAS __attribute__((address_space(1)))
; __device__ __forceinline__ void mem_unit(LAS unsigned char* lds, const bf16_t* Qb, const bf16_t* KVg, const bf16_t* Zb, bf16_t* Ob, int tid) {
;     ...
;     for (int d0 = 0; d0 < 16; ++d0) { const bf16x8 qf = *(const GAS bf16x8*)(Qw + d0 * 16); const int cb = (d0 * 32 + hi * 16) ^ ((r32 & 7) << 4);
; #pragma unroll
;         for (int kb = 0; kb < 8; ++kb) { const bf16x8 kf = *(const LAS bf16x8*)(lds + (kb * 32 + r32) * 512 + cb); p[kb] = __builtin_amdgcn_mfma_f32_32x32x16_bf16(kf, qf, p[kb], 0, 0, 0); } }
; #pragma unroll
;     for (int i = 0; i < 16; ++i) { const int ch = i * 512 + tid, key = ch >> 5, c16 = ch & 31; kv[i] = *(const GAS bf16x8*)((const GAS bf16_t*)KVg + (size_t)key * KVW + 1024 + c16 * 8); }
;     constexpr float C2 = 0.0625f * LOG2E;
;     float mx = p[0][0];
; #pragma unroll
;     for (int kb = 0; kb < 8; ++kb)
; #pragma unroll
;         for (int r = 0; r < 16; ++r) mx = fmaxf(mx, p[kb][r]);
;     { auto rr = __builtin_amdgcn_permlane32_swap(__float_as_uint(mx), __float_as_uint(mx), false, false); mx = fmaxf(__uint_as_float(rr[0]), __uint_as_float(rr[1])); }
	v_mfma_f32_32x32x16_bf16 v[114:129], v[164:167], v[232:235], v[114:129]
	ds_read_b128 v[164:167], v159 offset:16384
	s_waitcnt lgkmcnt(0)
	v_mfma_f32_32x32x16_bf16 v[98:113], v[164:167], v[232:235], v[98:113]
	ds_read_b128 v[164:167], v159 offset:32768
	s_waitcnt lgkmcnt(0)
	v_mfma_f32_32x32x16_bf16 v[82:97], v[164:167], v[232:235], v[82:97]
	ds_read_b128 v[164:167], v159 offset:49152
	s_waitcnt lgkmcnt(0)
	v_mfma_f32_32x32x16_bf16 v[66:81], v[164:167], v[232:235], v[66:81]
	v_add_u32_e32 v164, 0x10000, v159
	ds_read_b128 v[164:167], v164
	s_waitcnt lgkmcnt(0)
	v_mfma_f32_32x32x16_bf16 v[50:65], v[164:167], v[232:235], v[50:65]
	v_add_u32_e32 v164, 0x14000, v159
	ds_read_b128 v[164:167], v164
	s_waitcnt lgkmcnt(0)
	v_mfma_f32_32x32x16_bf16 v[34:49], v[164:167], v[232:235], v[34:49]
	v_add_u32_e32 v164, 0x18000, v159
	ds_read_b128 v[164:167], v164
	v_add_u32_e32 v159, 0x1c000, v159
	s_waitcnt lgkmcnt(0)
	v_mfma_f32_32x32x16_bf16 v[18:33], v[164:167], v[232:235], v[18:33]
	ds_read_b128 v[164:167], v159
	s_waitcnt lgkmcnt(0)
	v_mfma_f32_32x32x16_bf16 v[2:17], v[164:167], v[232:235], v[2:17]
	global_load_dwordx4 v[166:169], v[132:133], off offset:2048
	ds_read_b128 v[154:157], v158
	v_lshl_add_u64 v[132:133], v[130:131], 0, v[146:147]
	v_lshl_add_u64 v[132:133], v[132:133], 0, v[0:1]
	s_waitcnt vmcnt(1) lgkmcnt(0)
	v_mfma_f32_32x32x16_bf16 v[114:129], v[154:157], v[236:239], v[114:129]
	ds_read_b128 v[154:157], v158 offset:16384
	s_waitcnt lgkmcnt(0)
	v_mfma_f32_32x32x16_bf16 v[98:113], v[154:157], v[236:239], v[98:113]
	ds_read_b128 v[154:157], v158 offset:32768
	s_waitcnt lgkmcnt(0)
	v_mfma_f32_32x32x16_bf16 v[82:97], v[154:157], v[236:239], v[82:97]
	ds_read_b128 v[154:157], v158 offset:49152
	s_waitcnt lgkmcnt(0)
	v_mfma_f32_32x32x16_bf16 v[66:81], v[154:157], v[236:239], v[66:81]
	v_add_u32_e32 v154, 0x10000, v158
	ds_read_b128 v[154:157], v154
	s_waitcnt lgkmcnt(0)
	v_mfma_f32_32x32x16_bf16 v[50:65], v[154:157], v[236:239], v[50:65]
	v_add_u32_e32 v154, 0x14000, v158
	ds_read_b128 v[154:157], v154
	s_waitcnt lgkmcnt(0)
	v_mfma_f32_32x32x16_bf16 v[34:49], v[154:157], v[236:239], v[34:49]
	v_add_u32_e32 v154, 0x18000, v158
	ds_read_b128 v[154:157], v154
	s_waitcnt lgkmcnt(0)
	v_mfma_f32_32x32x16_bf16 v[18:33], v[154:157], v[236:239], v[18:33]
	v_add_u32_e32 v154, 0x1c000, v158
	ds_read_b128 v[154:157], v154
	s_waitcnt lgkmcnt(0)
	v_mfma_f32_32x32x16_bf16 v[2:17], v[154:157], v[236:239], v[2:17]
	global_load_dwordx4 v[162:165], v[132:133], off offset:2048
	v_lshl_add_u64 v[132:133], v[130:131], 0, v[148:149]
	v_lshl_add_u64 v[132:133], v[132:133], 0, v[0:1]
	global_load_dwordx4 v[158:161], v[132:133], off offset:2048
	v_lshl_add_u64 v[132:133], v[130:131], 0, v[150:151]
	v_lshl_add_u64 v[132:133], v[132:133], 0, v[0:1]
	global_load_dwordx4 v[154:157], v[132:133], off offset:2048
	v_lshl_add_u64 v[132:133], v[130:131], 0, v[152:153]
	v_lshl_add_u64 v[132:133], v[132:133], 0, v[0:1]
	global_load_dwordx4 v[150:153], v[132:133], off offset:2048
	v_lshl_add_u64 v[132:133], v[130:131], 0, v[202:203]
	v_lshl_add_u64 v[132:133], v[132:133], 0, v[0:1]
	global_load_dwordx4 v[146:149], v[132:133], off offset:2048
	v_lshl_add_u64 v[132:133], v[130:131], 0, v[204:205]
	v_lshl_add_u64 v[132:133], v[132:133], 0, v[0:1]
	global_load_dwordx4 v[142:145], v[132:133], off offset:2048
	v_lshl_add_u64 v[132:133], v[130:131], 0, v[206:207]
	v_lshl_add_u64 v[132:133], v[132:133], 0, v[0:1]
	global_load_dwordx4 v[138:141], v[132:133], off offset:2048
	v_lshl_add_u64 v[132:133], v[130:131], 0, v[208:209]
	v_lshl_add_u64 v[130:131], v[130:131], 0, v[210:211]
	v_lshl_add_u64 v[132:133], v[132:133], 0, v[0:1]
	v_lshl_add_u64 v[130:131], v[130:131], 0, v[0:1]
	v_max_f32_e32 v0, v115, v115
	v_max_f32_e32 v202, v114, v114
	v_max_f32_e32 v0, v202, v0
	v_max3_f32 v0, v0, v116, v117
	v_max3_f32 v0, v0, v118, v119
	v_max3_f32 v0, v0, v120, v121
	v_max3_f32 v0, v0, v122, v123
	v_max3_f32 v0, v0, v124, v125
	v_max3_f32 v0, v0, v126, v127
	v_max3_f32 v0, v0, v128, v129
	v_max3_f32 v0, v0, v98, v99
	v_max3_f32 v0, v0, v100, v101
	v_max3_f32 v0, v0, v102, v103
	v_max3_f32 v0, v0, v104, v105
	v_max3_f32 v0, v0, v106, v107
	v_max3_f32 v0, v0, v108, v109
	v_max3_f32 v0, v0, v110, v111
	v_max3_f32 v0, v0, v112, v113
	v_max3_f32 v0, v0, v82, v83
	v_max3_f32 v0, v0, v84, v85
	v_max3_f32 v0, v0, v86, v87
	v_max3_f32 v0, v0, v88, v89
	v_max3_f32 v0, v0, v90, v91
	v_max3_f32 v0, v0, v92, v93
	v_max3_f32 v0, v0, v94, v95
	v_max3_f32 v0, v0, v96, v97
	v_max3_f32 v0, v0, v66, v67
	v_max3_f32 v0, v0, v68, v69
	v_max3_f32 v0, v0, v70, v71
	v_max3_f32 v0, v0, v72, v73
	v_max3_f32 v0, v0, v74, v75
	v_max3_f32 v0, v0, v76, v77
	v_max3_f32 v0, v0, v78, v79
	v_max3_f32 v0, v0, v80, v81
	v_max3_f32 v0, v0, v50, v51
	v_max3_f32 v0, v0, v52, v53
	v_max3_f32 v0, v0, v54, v55
	v_max3_f32 v0, v0, v56, v57
	v_max3_f32 v0, v0, v58, v59
	v_max3_f32 v0, v0, v60, v61
	v_max3_f32 v0, v0, v62, v63
	v_max3_f32 v0, v0, v64, v65
	v_max3_f32 v0, v0, v34, v35
	v_max3_f32 v0, v0, v36, v37
	v_max3_f32 v0, v0, v38, v39
	v_max3_f32 v0, v0, v40, v41
	v_max3_f32 v0, v0, v42, v43
	v_max3_f32 v0, v0, v44, v45
	v_max3_f32 v0, v0, v46, v47
	v_max3_f32 v0, v0, v48, v49
	v_max3_f32 v0, v0, v18, v19
	v_max3_f32 v0, v0, v20, v21
	v_max3_f32 v0, v0, v22, v23
	v_max3_f32 v0, v0, v24, v25
	v_max3_f32 v0, v0, v26, v27
	v_max3_f32 v0, v0, v28, v29
	v_max3_f32 v0, v0, v30, v31
	v_max3_f32 v0, v0, v32, v33
	v_max3_f32 v0, v0, v2, v3
	v_max3_f32 v0, v0, v4, v5
	v_max3_f32 v0, v0, v6, v7
	v_max3_f32 v0, v0, v8, v9
	v_max3_f32 v0, v0, v10, v11
	v_max3_f32 v0, v0, v12, v13
	v_max3_f32 v0, v0, v14, v15
	v_max3_f32 v0, v0, v16, v17
; __device__ __forceinline__ void mem_unit(LAS unsigned char* lds, const bf16_t* Qb, const bf16_t* KVg, const bf16_t* Zb, bf16_t* Ob, int tid) {
;     ...
;     { auto rr = __builtin_amdgcn_permlane32_swap(__float_as_uint(mx), __float_as_uint(mx), false, false); mx = fmaxf(__uint_as_float(rr[0]), __uint_as_float(rr[1])); }
;     const float mc = -mx * C2; float ls = 0.f;
; #pragma unroll
;     for (int kb = 0; kb < 8; ++kb)
; #pragma unroll
;         for (int r = 0; r < 16; ++r) { const float e = __builtin_amdgcn_exp2f(fmaf(p[kb][r], C2, mc)); p[kb][r] = e; ls += e; }
	v_mov_b32_e32 v202, v0
	s_nop 1
	v_permlane32_swap_b32_e32 v0, v202
	v_max_f32_e32 v202, v202, v202
	v_max_f32_e32 v0, v0, v0
	v_max_f32_e32 v0, v0, v202
	v_mul_f32_e32 v202, 0xbdb8aa3b, v0
	v_fmamk_f32 v0, v114, 0x3db8aa3b, v202
	v_exp_f32_e32 v0, v0
	v_fmamk_f32 v114, v115, 0x3db8aa3b, v202
	v_exp_f32_e32 v114, v114
	v_fmamk_f32 v115, v116, 0x3db8aa3b, v202
	v_exp_f32_e32 v115, v115
	v_fmamk_f32 v116, v117, 0x3db8aa3b, v202
	v_exp_f32_e32 v116, v116
	v_fmamk_f32 v117, v118, 0x3db8aa3b, v202
	v_add_f32_e32 v203, 0, v0
	v_exp_f32_e32 v117, v117
	v_fmamk_f32 v118, v119, 0x3db8aa3b, v202
	v_add_f32_e32 v203, v114, v203
	v_exp_f32_e32 v118, v118
	v_fmamk_f32 v119, v120, 0x3db8aa3b, v202
	v_add_f32_e32 v203, v115, v203
	v_exp_f32_e32 v119, v119
	v_fmamk_f32 v120, v121, 0x3db8aa3b, v202
	v_add_f32_e32 v203, v116, v203
	v_exp_f32_e32 v120, v120
	v_fmamk_f32 v121, v122, 0x3db8aa3b, v202
	v_add_f32_e32 v203, v117, v203
	v_exp_f32_e32 v121, v121
	v_add_f32_e32 v203, v118, v203
	v_add_f32_e32 v203, v119, v203
	v_add_f32_e32 v203, v120, v203
	v_fmamk_f32 v123, v123, 0x3db8aa3b, v202
	v_add_f32_e32 v122, v121, v203
	v_exp_f32_e32 v203, v123
	v_fmamk_f32 v123, v124, 0x3db8aa3b, v202
	v_exp_f32_e32 v204, v123
	v_fmamk_f32 v123, v125, 0x3db8aa3b, v202
	v_exp_f32_e32 v205, v123
	v_fmamk_f32 v123, v126, 0x3db8aa3b, v202
	v_exp_f32_e32 v206, v123
	v_fmamk_f32 v123, v127, 0x3db8aa3b, v202
	v_add_f32_e32 v122, v203, v122
	v_exp_f32_e32 v207, v123
	v_fmamk_f32 v123, v128, 0x3db8aa3b, v202
	v_add_f32_e32 v122, v204, v122
	v_exp_f32_e32 v208, v123
	v_fmamk_f32 v123, v129, 0x3db8aa3b, v202
	v_add_f32_e32 v122, v205, v122
	v_exp_f32_e32 v129, v123
	v_fmamk_f32 v98, v98, 0x3db8aa3b, v202
	v_add_f32_e32 v122, v206, v122
	v_exp_f32_e32 v98, v98
	v_fmamk_f32 v99, v99, 0x3db8aa3b, v202
	v_add_f32_e32 v122, v207, v122
	v_exp_f32_e32 v99, v99
	v_fmamk_f32 v100, v100, 0x3db8aa3b, v202
	v_add_f32_e32 v122, v208, v122
	v_exp_f32_e32 v100, v100
	v_fmamk_f32 v101, v101, 0x3db8aa3b, v202
	v_add_f32_e32 v122, v129, v122
	v_exp_f32_e32 v101, v101
	v_fmamk_f32 v102, v102, 0x3db8aa3b, v202
	v_add_f32_e32 v122, v98, v122
	v_exp_f32_e32 v102, v102
	v_fmamk_f32 v103, v103, 0x3db8aa3b, v202
	v_add_f32_e32 v122, v99, v122
	v_exp_f32_e32 v103, v103
	v_fmamk_f32 v104, v104, 0x3db8aa3b, v202
	v_add_f32_e32 v122, v100, v122
	v_exp_f32_e32 v104, v104
	v_fmamk_f32 v105, v105, 0x3db8aa3b, v202
	v_add_f32_e32 v122, v101, v122
	v_exp_f32_e32 v105, v105
	v_fmamk_f32 v106, v106, 0x3db8aa3b, v202
	v_add_f32_e32 v122, v102, v122
	v_exp_f32_e32 v106, v106
	v_fmamk_f32 v107, v107, 0x3db8aa3b, v202
	v_add_f32_e32 v122, v103, v122
	v_exp_f32_e32 v107, v107
	v_fmamk_f32 v108, v108, 0x3db8aa3b, v202
	v_add_f32_e32 v122, v104, v122
	v_exp_f32_e32 v108, v108
	v_fmamk_f32 v109, v109, 0x3db8aa3b, v202
	v_add_f32_e32 v122, v105, v122
	v_exp_f32_e32 v109, v109
	v_fmamk_f32 v110, v110, 0x3db8aa3b, v202
	v_add_f32_e32 v122, v106, v122
	v_exp_f32_e32 v110, v110
	v_fmamk_f32 v111, v111, 0x3db8aa3b, v202
	v_add_f32_e32 v122, v107, v122
	v_exp_f32_e32 v111, v111
	v_fmamk_f32 v112, v112, 0x3db8aa3b, v202
	v_add_f32_e32 v122, v108, v122
	v_exp_f32_e32 v112, v112
	v_fmamk_f32 v113, v113, 0x3db8aa3b, v202
	v_add_f32_e32 v122, v109, v122
	v_exp_f32_e32 v113, v113
	v_fmamk_f32 v82, v82, 0x3db8aa3b, v202
	v_add_f32_e32 v122, v110, v122
	v_exp_f32_e32 v82, v82
	v_fmamk_f32 v83, v83, 0x3db8aa3b, v202
	v_add_f32_e32 v122, v111, v122
	v_exp_f32_e32 v83, v83
	v_fmamk_f32 v84, v84, 0x3db8aa3b, v202
	v_add_f32_e32 v122, v112, v122
	v_exp_f32_e32 v84, v84
	v_fmamk_f32 v85, v85, 0x3db8aa3b, v202
	v_add_f32_e32 v122, v113, v122
	v_exp_f32_e32 v85, v85
	v_fmamk_f32 v86, v86, 0x3db8aa3b, v202
	v_add_f32_e32 v122, v82, v122
	v_exp_f32_e32 v86, v86
	v_fmamk_f32 v87, v87, 0x3db8aa3b, v202
	v_add_f32_e32 v122, v83, v122
	v_exp_f32_e32 v87, v87
	v_fmamk_f32 v88, v88, 0x3db8aa3b, v202
	v_add_f32_e32 v122, v84, v122
	v_exp_f32_e32 v88, v88
	v_fmamk_f32 v89, v89, 0x3db8aa3b, v202
	v_add_f32_e32 v122, v85, v122
	v_exp_f32_e32 v89, v89
	v_fmamk_f32 v90, v90, 0x3db8aa3b, v202
	v_add_f32_e32 v122, v86, v122
	v_exp_f32_e32 v90, v90
	v_fmamk_f32 v91, v91, 0x3db8aa3b, v202
	v_add_f32_e32 v122, v87, v122
	v_exp_f32_e32 v91, v91
	v_fmamk_f32 v92, v92, 0x3db8aa3b, v202
	v_add_f32_e32 v122, v88, v122
	v_exp_f32_e32 v92, v92
	v_fmamk_f32 v93, v93, 0x3db8aa3b, v202
	v_add_f32_e32 v122, v89, v122
	v_exp_f32_e32 v93, v93
	v_fmamk_f32 v94, v94, 0x3db8aa3b, v202
	v_add_f32_e32 v122, v90, v122
	v_exp_f32_e32 v94, v94
	v_fmamk_f32 v95, v95, 0x3db8aa3b, v202
	v_add_f32_e32 v122, v91, v122
	v_exp_f32_e32 v95, v95
	v_fmamk_f32 v96, v96, 0x3db8aa3b, v202
	v_add_f32_e32 v122, v92, v122
	v_exp_f32_e32 v96, v96
	v_fmamk_f32 v97, v97, 0x3db8aa3b, v202
	v_add_f32_e32 v122, v93, v122
	v_exp_f32_e32 v97, v97
	v_fmamk_f32 v66, v66, 0x3db8aa3b, v202
	v_add_f32_e32 v122, v94, v122
	v_exp_f32_e32 v66, v66
	v_fmamk_f32 v67, v67, 0x3db8aa3b, v202
	v_add_f32_e32 v122, v95, v122
	v_exp_f32_e32 v67, v67
	v_fmamk_f32 v68, v68, 0x3db8aa3b, v202
	v_add_f32_e32 v122, v96, v122
	v_exp_f32_e32 v68, v68
	v_fmamk_f32 v69, v69, 0x3db8aa3b, v202
	v_add_f32_e32 v122, v97, v122
	v_exp_f32_e32 v69, v69
	v_fmamk_f32 v70, v70, 0x3db8aa3b, v202
	v_add_f32_e32 v122, v66, v122
	v_exp_f32_e32 v70, v70
	v_fmamk_f32 v71, v71, 0x3db8aa3b, v202
	v_add_f32_e32 v122, v67, v122
	v_exp_f32_e32 v71, v71
	v_fmamk_f32 v72, v72, 0x3db8aa3b, v202
	v_add_f32_e32 v122, v68, v122
	v_exp_f32_e32 v72, v72
	v_fmamk_f32 v73, v73, 0x3db8aa3b, v202
	v_add_f32_e32 v122, v69, v122
	v_exp_f32_e32 v73, v73
	v_fmamk_f32 v74, v74, 0x3db8aa3b, v202
	v_add_f32_e32 v122, v70, v122
	v_exp_f32_e32 v74, v74
; #define LAS __attribute__((address_space(3)))
; __device__ __forceinline__ int v_st(int k, int c) { const int kk = (k & ~0xC) | ((k & 4) << 1) | ((k & 8) >> 1); return ((kk >> 3) * 4 + (c >> 5)) * 512 + ((kk & 7) * 32 + (c & 31)) * 2; }
; __device__ __forceinline__ void mem_unit(LAS unsigned char* lds, const bf16_t* Qb, const bf16_t* KVg, const bf16_t* Zb, bf16_t* Ob, int tid) {
;     ...
;         for (int r = 0; r < 16; ++r) { const float e = __builtin_amdgcn_exp2f(fmaf(p[kb][r], C2, mc)); p[kb][r] = e; ls += e; }
;     { auto rr = __builtin_amdgcn_permlane32_swap(__float_as_uint(ls), __float_as_uint(ls), false, false); ls = __uint_as_float(rr[0]) + __uint_as_float(rr[1]); }
;     bf16x8 pa[4][4];
; #pragma unroll
;     for (int g = 0; g < 4; ++g) { FA_PK4(p[2 * g], 0, pa[g][0]); FA_PK4(p[2 * g], 8, pa[g][1]); FA_PK4(p[2 * g + 1], 0, pa[g][2]); FA_PK4(p[2 * g + 1], 8, pa[g][3]); }
;     __syncthreads();
; #pragma unroll
;     for (int i = 0; i < 16; ++i) { const int ch = i * 512 + tid, key = ch >> 5, c16 = ch & 31, d = c16 * 8;
;         *(LAS bf16x8*)(lds + ((key >> 6) * 2 + (d >> 7)) * 16384 + v_st(key & 63, d & 127)) = kv[i]; }
	v_fmamk_f32 v75, v75, 0x3db8aa3b, v202
	v_add_f32_e32 v122, v71, v122
	v_exp_f32_e32 v75, v75
	v_fmamk_f32 v76, v76, 0x3db8aa3b, v202
	v_add_f32_e32 v122, v72, v122
	v_exp_f32_e32 v76, v76
	v_fmamk_f32 v77, v77, 0x3db8aa3b, v202
	v_add_f32_e32 v122, v73, v122
	v_exp_f32_e32 v77, v77
	v_fmamk_f32 v78, v78, 0x3db8aa3b, v202
	v_add_f32_e32 v122, v74, v122
	v_exp_f32_e32 v78, v78
	v_fmamk_f32 v79, v79, 0x3db8aa3b, v202
	v_add_f32_e32 v122, v75, v122
	v_exp_f32_e32 v79, v79
	v_fmamk_f32 v80, v80, 0x3db8aa3b, v202
	v_add_f32_e32 v122, v76, v122
	v_exp_f32_e32 v80, v80
	v_fmamk_f32 v81, v81, 0x3db8aa3b, v202
	v_add_f32_e32 v122, v77, v122
	v_exp_f32_e32 v81, v81
	v_fmamk_f32 v50, v50, 0x3db8aa3b, v202
	v_add_f32_e32 v122, v78, v122
	v_exp_f32_e32 v50, v50
	v_fmamk_f32 v51, v51, 0x3db8aa3b, v202
	v_add_f32_e32 v122, v79, v122
	v_exp_f32_e32 v51, v51
	v_fmamk_f32 v52, v52, 0x3db8aa3b, v202
	v_add_f32_e32 v122, v80, v122
	v_exp_f32_e32 v52, v52
	v_fmamk_f32 v53, v53, 0x3db8aa3b, v202
	v_add_f32_e32 v122, v81, v122
	v_exp_f32_e32 v53, v53
	v_fmamk_f32 v54, v54, 0x3db8aa3b, v202
	v_add_f32_e32 v122, v50, v122
	v_exp_f32_e32 v54, v54
	v_fmamk_f32 v55, v55, 0x3db8aa3b, v202
	v_add_f32_e32 v122, v51, v122
	v_exp_f32_e32 v55, v55
	v_fmamk_f32 v56, v56, 0x3db8aa3b, v202
	v_add_f32_e32 v122, v52, v122
	v_exp_f32_e32 v56, v56
	v_fmamk_f32 v57, v57, 0x3db8aa3b, v202
	v_add_f32_e32 v122, v53, v122
	v_exp_f32_e32 v57, v57
	v_fmamk_f32 v58, v58, 0x3db8aa3b, v202
	v_add_f32_e32 v122, v54, v122
	v_exp_f32_e32 v58, v58
	v_fmamk_f32 v59, v59, 0x3db8aa3b, v202
	v_add_f32_e32 v122, v55, v122
	v_exp_f32_e32 v59, v59
	v_fmamk_f32 v60, v60, 0x3db8aa3b, v202
	v_add_f32_e32 v122, v56, v122
	v_exp_f32_e32 v60, v60
	v_fmamk_f32 v61, v61, 0x3db8aa3b, v202
	v_add_f32_e32 v122, v57, v122
	v_exp_f32_e32 v61, v61
	v_fmamk_f32 v62, v62, 0x3db8aa3b, v202
	v_add_f32_e32 v122, v58, v122
	v_exp_f32_e32 v62, v62
	v_fmamk_f32 v63, v63, 0x3db8aa3b, v202
	v_add_f32_e32 v122, v59, v122
	v_exp_f32_e32 v63, v63
	v_fmamk_f32 v64, v64, 0x3db8aa3b, v202
	v_add_f32_e32 v122, v60, v122
	v_exp_f32_e32 v64, v64
	v_fmamk_f32 v65, v65, 0x3db8aa3b, v202
	v_add_f32_e32 v122, v61, v122
	v_exp_f32_e32 v65, v65
	v_fmamk_f32 v34, v34, 0x3db8aa3b, v202
	v_add_f32_e32 v122, v62, v122
	v_exp_f32_e32 v34, v34
	v_fmamk_f32 v35, v35, 0x3db8aa3b, v202
	v_add_f32_e32 v122, v63, v122
	v_exp_f32_e32 v35, v35
	v_fmamk_f32 v36, v36, 0x3db8aa3b, v202
	v_add_f32_e32 v122, v64, v122
	v_exp_f32_e32 v36, v36
	v_fmamk_f32 v37, v37, 0x3db8aa3b, v202
	v_add_f32_e32 v122, v65, v122
	v_exp_f32_e32 v37, v37
	v_fmamk_f32 v38, v38, 0x3db8aa3b, v202
	v_add_f32_e32 v122, v34, v122
	v_exp_f32_e32 v38, v38
	v_fmamk_f32 v39, v39, 0x3db8aa3b, v202
	v_add_f32_e32 v122, v35, v122
	v_exp_f32_e32 v39, v39
	v_fmamk_f32 v40, v40, 0x3db8aa3b, v202
	v_add_f32_e32 v122, v36, v122
	v_exp_f32_e32 v40, v40
	v_fmamk_f32 v41, v41, 0x3db8aa3b, v202
	v_add_f32_e32 v122, v37, v122
	v_exp_f32_e32 v41, v41
	v_fmamk_f32 v42, v42, 0x3db8aa3b, v202
	v_add_f32_e32 v122, v38, v122
	v_exp_f32_e32 v42, v42
	v_fmamk_f32 v43, v43, 0x3db8aa3b, v202
	v_add_f32_e32 v122, v39, v122
	v_exp_f32_e32 v43, v43
	v_fmamk_f32 v44, v44, 0x3db8aa3b, v202
	v_add_f32_e32 v122, v40, v122
	v_exp_f32_e32 v44, v44
	v_fmamk_f32 v45, v45, 0x3db8aa3b, v202
	v_add_f32_e32 v122, v41, v122
	v_exp_f32_e32 v45, v45
	v_fmamk_f32 v46, v46, 0x3db8aa3b, v202
	v_add_f32_e32 v122, v42, v122
	v_exp_f32_e32 v46, v46
	v_fmamk_f32 v47, v47, 0x3db8aa3b, v202
	v_add_f32_e32 v122, v43, v122
	v_exp_f32_e32 v47, v47
	v_fmamk_f32 v48, v48, 0x3db8aa3b, v202
	v_add_f32_e32 v122, v44, v122
	v_exp_f32_e32 v48, v48
	v_fmamk_f32 v49, v49, 0x3db8aa3b, v202
	v_add_f32_e32 v122, v45, v122
	v_exp_f32_e32 v49, v49
	v_fmamk_f32 v18, v18, 0x3db8aa3b, v202
	v_add_f32_e32 v122, v46, v122
	v_exp_f32_e32 v18, v18
	v_fmamk_f32 v19, v19, 0x3db8aa3b, v202
	v_add_f32_e32 v122, v47, v122
	v_exp_f32_e32 v19, v19
	v_fmamk_f32 v20, v20, 0x3db8aa3b, v202
	v_add_f32_e32 v122, v48, v122
	v_exp_f32_e32 v20, v20
	v_fmamk_f32 v21, v21, 0x3db8aa3b, v202
	v_add_f32_e32 v122, v49, v122
	v_exp_f32_e32 v21, v21
	v_fmamk_f32 v22, v22, 0x3db8aa3b, v202
	v_add_f32_e32 v122, v18, v122
	v_exp_f32_e32 v22, v22
	v_fmamk_f32 v23, v23, 0x3db8aa3b, v202
	v_add_f32_e32 v122, v19, v122
	v_exp_f32_e32 v23, v23
	v_fmamk_f32 v24, v24, 0x3db8aa3b, v202
	v_add_f32_e32 v122, v20, v122
	v_exp_f32_e32 v24, v24
	v_fmamk_f32 v25, v25, 0x3db8aa3b, v202
	v_add_f32_e32 v122, v21, v122
	v_exp_f32_e32 v25, v25
	v_fmamk_f32 v26, v26, 0x3db8aa3b, v202
	v_add_f32_e32 v122, v22, v122
	v_exp_f32_e32 v26, v26
	v_fmamk_f32 v27, v27, 0x3db8aa3b, v202
	v_add_f32_e32 v122, v23, v122
	v_exp_f32_e32 v27, v27
	v_fmamk_f32 v28, v28, 0x3db8aa3b, v202
	v_add_f32_e32 v122, v24, v122
	v_exp_f32_e32 v28, v28
	v_fmamk_f32 v29, v29, 0x3db8aa3b, v202
	v_add_f32_e32 v122, v25, v122
	v_exp_f32_e32 v29, v29
	v_fmamk_f32 v30, v30, 0x3db8aa3b, v202
	v_add_f32_e32 v122, v26, v122
	v_exp_f32_e32 v30, v30
	v_fmamk_f32 v31, v31, 0x3db8aa3b, v202
	v_add_f32_e32 v122, v27, v122
	v_exp_f32_e32 v31, v31
	v_fmamk_f32 v32, v32, 0x3db8aa3b, v202
	v_add_f32_e32 v122, v28, v122
	v_exp_f32_e32 v32, v32
	v_fmamk_f32 v33, v33, 0x3db8aa3b, v202
	v_add_f32_e32 v122, v29, v122
	v_exp_f32_e32 v33, v33
	v_fmamk_f32 v2, v2, 0x3db8aa3b, v202
	v_add_f32_e32 v122, v30, v122
	v_exp_f32_e32 v2, v2
	v_fmamk_f32 v3, v3, 0x3db8aa3b, v202
	v_add_f32_e32 v122, v31, v122
	v_exp_f32_e32 v3, v3
	v_fmamk_f32 v4, v4, 0x3db8aa3b, v202
	v_add_f32_e32 v122, v32, v122
	v_exp_f32_e32 v4, v4
	v_fmamk_f32 v5, v5, 0x3db8aa3b, v202
	v_add_f32_e32 v122, v33, v122
	v_exp_f32_e32 v5, v5
	v_fmamk_f32 v6, v6, 0x3db8aa3b, v202
	v_add_f32_e32 v122, v2, v122
	v_exp_f32_e32 v6, v6
	v_fmamk_f32 v7, v7, 0x3db8aa3b, v202
	v_add_f32_e32 v122, v3, v122
	v_exp_f32_e32 v7, v7
	v_fmamk_f32 v8, v8, 0x3db8aa3b, v202
	v_add_f32_e32 v122, v4, v122
	v_exp_f32_e32 v209, v8
	v_add_f32_e32 v122, v5, v122
	v_add_f32_e32 v122, v6, v122
	v_add_f32_e32 v122, v7, v122
	v_cvt_pk_bf16_f32 v123, v115, v116
	v_cvt_pk_bf16_f32 v116, v102, v103
	v_cvt_pk_bf16_f32 v103, v76, v77
	v_cvt_pk_bf16_f32 v76, v6, v7
	v_lshrrev_b32_e32 v6, 5, v228
	v_add_f32_e32 v8, v209, v122
	v_cvt_pk_bf16_f32 v122, v0, v114
	v_lshrrev_b32_e32 v0, 4, v228
	v_and_b32_e32 v6, 48, v6
	v_and_or_b32 v0, v0, 8, v6
	v_cvt_pk_bf16_f32 v102, v74, v75
	v_cvt_pk_bf16_f32 v74, v2, v3
	v_bfe_u32 v2, v228, 4, 1
	v_bfe_u32 v3, v228, 2, 2
	v_lshrrev_b32_e32 v7, 10, v228
	v_lshrrev_b32_e32 v0, 1, v0
	v_and_or_b32 v7, v7, s28, v2
	v_or_b32_e32 v0, v0, v3
	v_cvt_pk_bf16_f32 v75, v4, v5
	v_and_b32_e32 v4, 0x100, v228
	v_lshl_add_u32 v7, v7, 14, 0
	v_lshlrev_b32_e32 v0, 9, v0
	v_lshlrev_b32_e32 v6, 1, v228
	v_and_b32_e32 v5, 48, v231
	v_and_b32_e32 v6, 0xc0, v6
	v_add3_u32 v0, v7, v0, v4
	v_add3_u32 v0, v0, v6, v5
	global_load_dwordx4 v[134:137], v[132:133], off offset:2048
	v_lshrrev_b32_e32 v7, 4, v230
	global_load_dwordx4 v[130:133], v[130:131], off offset:2048
	s_barrier
; #define LAS __attribute__((address_space(3)))
; __device__ __forceinline__ int v_st(int k, int c) { const int kk = (k & ~0xC) | ((k & 4) << 1) | ((k & 8) >> 1); return ((kk >> 3) * 4 + (c >> 5)) * 512 + ((kk & 7) * 32 + (c & 31)) * 2; }
; __device__ __forceinline__ void mem_unit(LAS unsigned char* lds, const bf16_t* Qb, const bf16_t* KVg, const bf16_t* Zb, bf16_t* Ob, int tid) {
;     ...
;     for (int i = 0; i < 16; ++i) { const int ch = i * 512 + tid, key = ch >> 5, c16 = ch & 31, d = c16 * 8;
;         *(LAS bf16x8*)(lds + ((key >> 6) * 2 + (d >> 7)) * 16384 + v_st(key & 63, d & 127)) = kv[i]; }
	ds_write_b128 v0, v[190:193]
	v_lshrrev_b32_e32 v0, 5, v230
	v_and_b32_e32 v0, 48, v0
	v_and_or_b32 v0, v7, 8, v0
	v_lshrrev_b32_e32 v6, 10, v230
	v_lshrrev_b32_e32 v0, 1, v0
	v_and_or_b32 v6, v6, s28, v2
	v_or_b32_e32 v0, v0, v3
	v_lshl_add_u32 v6, v6, 14, 0
	v_lshlrev_b32_e32 v0, 9, v0
	v_lshlrev_b32_e32 v7, 1, v230
	v_and_b32_e32 v7, 0xc0, v7
	v_add3_u32 v0, v6, v0, v4
	v_add3_u32 v0, v0, v7, v5
	ds_write_b128 v0, v[186:189]
	v_lshrrev_b32_e32 v0, 5, v229
	v_and_b32_e32 v0, 48, v0
	v_lshrrev_b32_e32 v7, 4, v229
	v_and_or_b32 v0, v7, 8, v0
	v_lshrrev_b32_e32 v6, 10, v229
	v_lshrrev_b32_e32 v0, 1, v0
	v_and_or_b32 v6, v6, s28, v2
	v_or_b32_e32 v0, v0, v3
	v_lshl_add_u32 v6, v6, 14, 0
	v_lshlrev_b32_e32 v0, 9, v0
	v_lshlrev_b32_e32 v7, 1, v229
	v_and_b32_e32 v7, 0xc0, v7
	v_add3_u32 v0, v6, v0, v4
	v_add3_u32 v0, v0, v7, v5
	ds_write_b128 v0, v[182:185]
	v_lshrrev_b32_e32 v0, 5, v227
	v_and_b32_e32 v0, 48, v0
	v_lshrrev_b32_e32 v7, 4, v227
	v_and_or_b32 v0, v7, 8, v0
	v_lshrrev_b32_e32 v6, 10, v227
	v_lshrrev_b32_e32 v0, 1, v0
	v_and_or_b32 v6, v6, s28, v2
	v_or_b32_e32 v0, v0, v3
	v_lshl_add_u32 v6, v6, 14, 0
	v_lshlrev_b32_e32 v0, 9, v0
	v_lshlrev_b32_e32 v7, 1, v227
	v_and_b32_e32 v7, 0xc0, v7
	v_add3_u32 v0, v6, v0, v4
	v_add3_u32 v0, v0, v7, v5
	ds_write_b128 v0, v[178:181]
	v_lshrrev_b32_e32 v0, 5, v226
	v_and_b32_e32 v0, 48, v0
	v_lshrrev_b32_e32 v7, 4, v226
	v_and_or_b32 v0, v7, 8, v0
	v_lshrrev_b32_e32 v6, 10, v226
	v_lshrrev_b32_e32 v0, 1, v0
	v_and_or_b32 v6, v6, s28, v2
	v_or_b32_e32 v0, v0, v3
	v_lshl_add_u32 v6, v6, 14, 0
	v_lshlrev_b32_e32 v0, 9, v0
	v_lshlrev_b32_e32 v7, 1, v226
	v_and_b32_e32 v7, 0xc0, v7
	v_add3_u32 v0, v6, v0, v4
	v_add3_u32 v0, v0, v7, v5
	ds_write_b128 v0, v[174:177]
	v_lshrrev_b32_e32 v0, 5, v225
	v_and_b32_e32 v0, 48, v0
	v_lshrrev_b32_e32 v7, 4, v225
	v_and_or_b32 v0, v7, 8, v0
	v_lshrrev_b32_e32 v6, 10, v225
	v_lshrrev_b32_e32 v0, 1, v0
	v_and_or_b32 v6, v6, s28, v2
	v_or_b32_e32 v0, v0, v3
	v_lshl_add_u32 v6, v6, 14, 0
	v_lshlrev_b32_e32 v0, 9, v0
	v_lshlrev_b32_e32 v7, 1, v225
	v_and_b32_e32 v7, 0xc0, v7
	v_add3_u32 v0, v6, v0, v4
	v_add3_u32 v0, v0, v7, v5
	ds_write_b128 v0, v[170:173]
	v_lshrrev_b32_e32 v0, 5, v224
	v_and_b32_e32 v0, 48, v0
	v_lshrrev_b32_e32 v7, 4, v224
	v_and_or_b32 v0, v7, 8, v0
	v_lshrrev_b32_e32 v6, 10, v224
	v_lshrrev_b32_e32 v0, 1, v0
	v_and_or_b32 v6, v6, s28, v2
	v_or_b32_e32 v0, v0, v3
	v_lshl_add_u32 v6, v6, 14, 0
	v_lshlrev_b32_e32 v0, 9, v0
	v_lshlrev_b32_e32 v7, 1, v224
	v_and_b32_e32 v7, 0xc0, v7
	v_add3_u32 v0, v6, v0, v4
	v_add3_u32 v0, v0, v7, v5
	s_waitcnt vmcnt(9)
	ds_write_b128 v0, v[166:169]
	v_lshrrev_b32_e32 v0, 5, v223
	v_and_b32_e32 v0, 48, v0
	v_lshrrev_b32_e32 v7, 4, v223
	v_and_or_b32 v0, v7, 8, v0
	v_lshrrev_b32_e32 v6, 10, v223
	v_lshrrev_b32_e32 v0, 1, v0
	v_and_or_b32 v6, v6, s28, v2
	v_or_b32_e32 v0, v0, v3
	v_lshl_add_u32 v6, v6, 14, 0
	v_lshlrev_b32_e32 v0, 9, v0
	v_lshlrev_b32_e32 v7, 1, v223
	v_and_b32_e32 v7, 0xc0, v7
	v_add3_u32 v0, v6, v0, v4
	v_add3_u32 v0, v0, v7, v5
	s_waitcnt vmcnt(8)
	ds_write_b128 v0, v[162:165]
	v_lshrrev_b32_e32 v0, 5, v222
	v_and_b32_e32 v0, 48, v0
	v_lshrrev_b32_e32 v7, 4, v222
	v_and_or_b32 v0, v7, 8, v0
	v_lshrrev_b32_e32 v6, 10, v222
	v_lshrrev_b32_e32 v0, 1, v0
	v_and_or_b32 v6, v6, s28, v2
	v_or_b32_e32 v0, v0, v3
	v_lshl_add_u32 v6, v6, 14, 0
	v_lshlrev_b32_e32 v0, 9, v0
	v_lshlrev_b32_e32 v7, 1, v222
	v_and_b32_e32 v7, 0xc0, v7
	v_add3_u32 v0, v6, v0, v4
	v_add3_u32 v0, v0, v7, v5
	s_waitcnt vmcnt(7)
	ds_write_b128 v0, v[158:161]
	v_lshrrev_b32_e32 v0, 5, v221
	v_and_b32_e32 v0, 48, v0
	v_lshrrev_b32_e32 v7, 4, v221
	v_and_or_b32 v0, v7, 8, v0
	v_lshrrev_b32_e32 v6, 10, v221
	v_lshrrev_b32_e32 v0, 1, v0
	v_and_or_b32 v6, v6, s28, v2
	v_or_b32_e32 v0, v0, v3
	v_lshl_add_u32 v6, v6, 14, 0
	v_lshlrev_b32_e32 v0, 9, v0
	v_lshlrev_b32_e32 v7, 1, v221
	v_and_b32_e32 v7, 0xc0, v7
	v_add3_u32 v0, v6, v0, v4
	v_add3_u32 v0, v0, v7, v5
	s_waitcnt vmcnt(6)
	ds_write_b128 v0, v[154:157]
	v_lshrrev_b32_e32 v0, 5, v220
	v_and_b32_e32 v0, 48, v0
	v_lshrrev_b32_e32 v7, 4, v220
	v_and_or_b32 v0, v7, 8, v0
	v_lshrrev_b32_e32 v6, 10, v220
	v_lshrrev_b32_e32 v0, 1, v0
	v_and_or_b32 v6, v6, s28, v2
	v_or_b32_e32 v0, v0, v3
	v_lshl_add_u32 v6, v6, 14, 0
	v_lshlrev_b32_e32 v0, 9, v0
	v_lshlrev_b32_e32 v7, 1, v220
	v_and_b32_e32 v7, 0xc0, v7
	v_add3_u32 v0, v6, v0, v4
	v_add3_u32 v0, v0, v7, v5
	s_waitcnt vmcnt(5)
	ds_write_b128 v0, v[150:153]
	v_lshrrev_b32_e32 v0, 5, v219
	v_and_b32_e32 v0, 48, v0
	v_lshrrev_b32_e32 v7, 4, v219
	v_and_or_b32 v0, v7, 8, v0
	v_lshrrev_b32_e32 v6, 10, v219
	v_lshrrev_b32_e32 v0, 1, v0
	v_and_or_b32 v6, v6, s28, v2
	v_or_b32_e32 v0, v0, v3
	v_lshl_add_u32 v6, v6, 14, 0
	v_lshlrev_b32_e32 v0, 9, v0
	v_lshlrev_b32_e32 v7, 1, v219
	v_and_b32_e32 v7, 0xc0, v7
	v_add3_u32 v0, v6, v0, v4
	v_add3_u32 v0, v0, v7, v5
	s_waitcnt vmcnt(4)
	ds_write_b128 v0, v[146:149]
	v_lshrrev_b32_e32 v0, 5, v218
	v_and_b32_e32 v0, 48, v0
	v_lshrrev_b32_e32 v7, 4, v218
	v_and_or_b32 v0, v7, 8, v0
	v_lshrrev_b32_e32 v6, 10, v218
	v_lshrrev_b32_e32 v0, 1, v0
	v_and_or_b32 v6, v6, s28, v2
	v_or_b32_e32 v0, v0, v3
	v_lshl_add_u32 v6, v6, 14, 0
	v_lshlrev_b32_e32 v0, 9, v0
	v_lshlrev_b32_e32 v7, 1, v218
	v_and_b32_e32 v7, 0xc0, v7
	v_add3_u32 v0, v6, v0, v4
	v_add3_u32 v0, v0, v7, v5
	s_waitcnt vmcnt(3)
; #define LAS __attribute__((address_space(3)))
; __device__ __forceinline__ int v_st(int k, int c) { const int kk = (k & ~0xC) | ((k & 4) << 1) | ((k & 8) >> 1); return ((kk >> 3) * 4 + (c >> 5)) * 512 + ((kk & 7) * 32 + (c & 31)) * 2; }
; __device__ __forceinline__ int v_rd_base(int lane) { return ((lane & 3) << 3) | (((lane >> 2) & 3) << 6) | (((lane >> 4) & 1) << 5) | (((lane >> 5) & 1) << 8); }
; __device__ __forceinline__ void mem_unit(LAS unsigned char* lds, const bf16_t* Qb, const bf16_t* KVg, const bf16_t* Zb, bf16_t* Ob, int tid) {
;     ...
; #pragma unroll
;     for (int kb = 0; kb < 8; ++kb)
; #pragma unroll
;         for (int r = 0; r < 16; ++r) { const float e = __builtin_amdgcn_exp2f(fmaf(p[kb][r], C2, mc)); p[kb][r] = e; ls += e; }
;     { auto rr = __builtin_amdgcn_permlane32_swap(__float_as_uint(ls), __float_as_uint(ls), false, false); ls = __uint_as_float(rr[0]) + __uint_as_float(rr[1]); }
;     bf16x8 pa[4][4];
; #pragma unroll
;     for (int g = 0; g < 4; ++g) { FA_PK4(p[2 * g], 0, pa[g][0]); FA_PK4(p[2 * g], 8, pa[g][1]); FA_PK4(p[2 * g + 1], 0, pa[g][2]); FA_PK4(p[2 * g + 1], 8, pa[g][3]); }
;     __syncthreads();
; #pragma unroll
;     for (int i = 0; i < 16; ++i) { const int ch = i * 512 + tid, key = ch >> 5, c16 = ch & 31, d = c16 * 8;
;         *(LAS bf16x8*)(lds + ((key >> 6) * 2 + (d >> 7)) * 16384 + v_st(key & 63, d & 127)) = kv[i]; }
;     __syncthreads();
;     const int vb0 = (int)(unsigned)(size_t)lds + v_rd_base(lane);
;     LAS float* li_l = (LAS float*)(lds + OFF_WS_MEM) + wid * 32;
;     if (hi == 0) li_l[r32] = ls; asm volatile("s_waitcnt lgkmcnt(0)" ::: "memory");
	ds_write_b128 v0, v[142:145]
	v_lshrrev_b32_e32 v0, 5, v217
	v_and_b32_e32 v0, 48, v0
	v_lshrrev_b32_e32 v7, 4, v217
	v_and_or_b32 v0, v7, 8, v0
	v_lshrrev_b32_e32 v6, 10, v217
	v_lshrrev_b32_e32 v0, 1, v0
	v_and_or_b32 v6, v6, s28, v2
	v_or_b32_e32 v0, v0, v3
	v_lshl_add_u32 v6, v6, 14, 0
	v_lshlrev_b32_e32 v0, 9, v0
	v_lshlrev_b32_e32 v7, 1, v217
	v_and_b32_e32 v7, 0xc0, v7
	v_add3_u32 v0, v6, v0, v4
	v_add3_u32 v0, v0, v7, v5
	v_fmamk_f32 v9, v9, 0x3db8aa3b, v202
	s_waitcnt vmcnt(2)
	ds_write_b128 v0, v[138:141]
	v_lshrrev_b32_e32 v0, 5, v216
	v_exp_f32_e32 v210, v9
	v_fmamk_f32 v9, v10, 0x3db8aa3b, v202
	v_and_b32_e32 v0, 48, v0
	v_lshrrev_b32_e32 v7, 4, v216
	v_exp_f32_e32 v10, v9
	v_fmamk_f32 v9, v11, 0x3db8aa3b, v202
	v_and_or_b32 v0, v7, 8, v0
	v_exp_f32_e32 v11, v9
	v_fmamk_f32 v9, v12, 0x3db8aa3b, v202
	v_lshrrev_b32_e32 v6, 10, v216
	v_lshrrev_b32_e32 v0, 1, v0
	v_exp_f32_e32 v12, v9
	v_fmamk_f32 v9, v13, 0x3db8aa3b, v202
	v_and_or_b32 v6, v6, s28, v2
	v_or_b32_e32 v0, v0, v3
	v_add_f32_e32 v8, v210, v8
	v_exp_f32_e32 v13, v9
	v_fmamk_f32 v9, v14, 0x3db8aa3b, v202
	v_lshl_add_u32 v6, v6, 14, 0
	v_lshlrev_b32_e32 v0, 9, v0
	v_lshlrev_b32_e32 v7, 1, v216
	v_add_f32_e32 v8, v10, v8
	v_exp_f32_e32 v14, v9
	v_fmamk_f32 v9, v15, 0x3db8aa3b, v202
	v_and_b32_e32 v7, 0xc0, v7
	v_add3_u32 v0, v6, v0, v4
	v_add_f32_e32 v8, v11, v8
	v_exp_f32_e32 v15, v9
	v_fmamk_f32 v9, v16, 0x3db8aa3b, v202
	v_add3_u32 v0, v0, v7, v5
	v_add_f32_e32 v8, v12, v8
	v_exp_f32_e32 v16, v9
	v_fmac_f32_e32 v202, 0x3db8aa3b, v17
	s_waitcnt vmcnt(1)
	ds_write_b128 v0, v[134:137]
	v_lshrrev_b32_e32 v0, 5, v215
	v_lshrrev_b32_e32 v6, 10, v215
	v_add_f32_e32 v8, v13, v8
	v_exp_f32_e32 v17, v202
	v_and_or_b32 v2, v6, s28, v2
	v_and_b32_e32 v0, 48, v0
	v_lshrrev_b32_e32 v6, 4, v215
	v_add_f32_e32 v8, v14, v8
	v_and_or_b32 v0, v6, 8, v0
	v_add_f32_e32 v8, v15, v8
	v_lshrrev_b32_e32 v0, 1, v0
	v_add_f32_e32 v8, v16, v8
	v_or_b32_e32 v0, v0, v3
	v_add_f32_e32 v8, v17, v8
	v_lshl_add_u32 v2, v2, 14, 0
	v_lshlrev_b32_e32 v0, 9, v0
	v_lshlrev_b32_e32 v3, 1, v215
	v_mov_b32_e32 v9, v8
	v_cvt_pk_bf16_f32 v124, v117, v118
	v_cvt_pk_bf16_f32 v125, v119, v120
	v_cvt_pk_bf16_f32 v126, v121, v203
	v_cvt_pk_bf16_f32 v127, v204, v205
	v_cvt_pk_bf16_f32 v128, v206, v207
	v_cvt_pk_bf16_f32 v129, v208, v129
	v_cvt_pk_bf16_f32 v114, v98, v99
	v_cvt_pk_bf16_f32 v115, v100, v101
	v_cvt_pk_bf16_f32 v117, v104, v105
	v_cvt_pk_bf16_f32 v118, v106, v107
	v_cvt_pk_bf16_f32 v119, v108, v109
	v_cvt_pk_bf16_f32 v120, v110, v111
	v_cvt_pk_bf16_f32 v121, v112, v113
	v_cvt_pk_bf16_f32 v106, v82, v83
	v_cvt_pk_bf16_f32 v107, v84, v85
	v_cvt_pk_bf16_f32 v108, v86, v87
	v_cvt_pk_bf16_f32 v109, v88, v89
	v_cvt_pk_bf16_f32 v110, v90, v91
	v_cvt_pk_bf16_f32 v111, v92, v93
	v_cvt_pk_bf16_f32 v112, v94, v95
	v_cvt_pk_bf16_f32 v113, v96, v97
	v_cvt_pk_bf16_f32 v98, v66, v67
	v_cvt_pk_bf16_f32 v99, v68, v69
	v_cvt_pk_bf16_f32 v100, v70, v71
	v_cvt_pk_bf16_f32 v101, v72, v73
	v_cvt_pk_bf16_f32 v104, v78, v79
	v_cvt_pk_bf16_f32 v105, v80, v81
	v_cvt_pk_bf16_f32 v90, v50, v51
	v_cvt_pk_bf16_f32 v91, v52, v53
	v_cvt_pk_bf16_f32 v92, v54, v55
	v_cvt_pk_bf16_f32 v93, v56, v57
	v_cvt_pk_bf16_f32 v94, v58, v59
	v_cvt_pk_bf16_f32 v95, v60, v61
	v_cvt_pk_bf16_f32 v96, v62, v63
	v_cvt_pk_bf16_f32 v97, v64, v65
	v_cvt_pk_bf16_f32 v82, v34, v35
	v_cvt_pk_bf16_f32 v83, v36, v37
	v_cvt_pk_bf16_f32 v84, v38, v39
	v_cvt_pk_bf16_f32 v85, v40, v41
	v_cvt_pk_bf16_f32 v86, v42, v43
	v_cvt_pk_bf16_f32 v87, v44, v45
	v_cvt_pk_bf16_f32 v88, v46, v47
	v_cvt_pk_bf16_f32 v89, v48, v49
	v_cvt_pk_bf16_f32 v66, v18, v19
	v_cvt_pk_bf16_f32 v67, v20, v21
	v_cvt_pk_bf16_f32 v68, v22, v23
	v_cvt_pk_bf16_f32 v69, v24, v25
	v_cvt_pk_bf16_f32 v70, v26, v27
	v_cvt_pk_bf16_f32 v71, v28, v29
	v_cvt_pk_bf16_f32 v72, v30, v31
	v_cvt_pk_bf16_f32 v73, v32, v33
	v_cvt_pk_bf16_f32 v77, v209, v210
	v_cvt_pk_bf16_f32 v78, v10, v11
	v_cvt_pk_bf16_f32 v79, v12, v13
	v_cvt_pk_bf16_f32 v80, v14, v15
	v_cvt_pk_bf16_f32 v81, v16, v17
	v_and_b32_e32 v3, 0xc0, v3
	v_add3_u32 v0, v2, v0, v4
	v_permlane32_swap_b32_e32 v8, v9
	v_permlane32_swap_b32_e32 v122, v124
	v_permlane32_swap_b32_e32 v123, v125
	v_permlane32_swap_b32_e32 v126, v128
	v_permlane32_swap_b32_e32 v127, v129
	v_permlane32_swap_b32_e32 v114, v116
	v_permlane32_swap_b32_e32 v115, v117
	v_permlane32_swap_b32_e32 v118, v120
	v_permlane32_swap_b32_e32 v119, v121
	v_permlane32_swap_b32_e32 v106, v108
	v_permlane32_swap_b32_e32 v107, v109
	v_permlane32_swap_b32_e32 v110, v112
	v_permlane32_swap_b32_e32 v111, v113
	v_permlane32_swap_b32_e32 v98, v100
	v_permlane32_swap_b32_e32 v99, v101
	v_permlane32_swap_b32_e32 v102, v104
	v_permlane32_swap_b32_e32 v103, v105
	v_permlane32_swap_b32_e32 v90, v92
	v_permlane32_swap_b32_e32 v91, v93
	v_permlane32_swap_b32_e32 v94, v96
	v_permlane32_swap_b32_e32 v95, v97
	v_permlane32_swap_b32_e32 v82, v84
	v_permlane32_swap_b32_e32 v83, v85
	v_permlane32_swap_b32_e32 v86, v88
	v_permlane32_swap_b32_e32 v87, v89
	v_permlane32_swap_b32_e32 v66, v68
	v_permlane32_swap_b32_e32 v67, v69
	v_permlane32_swap_b32_e32 v70, v72
	v_permlane32_swap_b32_e32 v71, v73
	v_permlane32_swap_b32_e32 v74, v76
	v_permlane32_swap_b32_e32 v75, v77
	v_permlane32_swap_b32_e32 v78, v80
	v_permlane32_swap_b32_e32 v79, v81
	v_add3_u32 v0, v0, v3, v5
	s_waitcnt vmcnt(0)
	ds_write_b128 v0, v[130:133]
	s_waitcnt lgkmcnt(0)
	s_barrier
	s_and_saveexec_b64 s[4:5], vcc
	s_cbranch_execz .LBB0_543
	v_add_f32_e32 v0, v8, v9
	v_lshl_add_u32 v2, v214, 2, s12
	ds_write_b32 v2, v0
	s_branch .LBB0_543
